# UP epilogue rewritten for row-interleaved accumulators (A rows staged as 4*fr+m): conv taps in-lane, 2 VALU/elt instead of 4.5
# speedup vs baseline: 1.0269x; 1.0269x over previous
.LBB0_549:
	s_add_u32 s54, s88, 0x900000
	s_addc_u32 s55, s89, 0
	s_ashr_i32 s29, s28, 31
	v_lshrrev_b32_e32 v3, 1, v170
	s_lshl_b64 s[6:7], s[28:29], 19
	v_and_b32_e32 v14, 24, v3
	v_lshrrev_b32_e32 v3, 5, v170
	s_add_u32 s8, s68, s6
	v_and_b32_e32 v3, 4, v3
	v_bfe_u32 v4, v170, 2, 2
	s_addc_u32 s9, s69, s7
	s_ashr_i32 s47, s46, 31
	v_lshlrev_b32_e32 v1, 4, v170
	v_and_b32_e32 v2, 32, v170
	v_bfe_u32 v12, v170, 2, 4
	v_or3_b32 v3, v3, v4, v14
	v_lshrrev_b32_e32 v4, 3, v170
	s_movk_i32 s13, 0x70
	v_writelane_b32 v255, s48, 16
	s_lshl_b64 s[6:7], s[46:47], 19
	v_bitop3_b32 v10, v1, v2, 48 bitop3:0x6c
	v_and_b32_e32 v11, 64, v170
	v_and_or_b32 v5, v4, s13, v12
	s_movk_i32 s13, 0x60
	v_add_u32_e32 v13, 0x2000, v1
	v_writelane_b32 v255, s49, 17
	s_add_u32 s48, s54, s6
	v_or_b32_e32 v2, v10, v11
	v_and_or_b32 v4, v4, s13, v3
	v_lshrrev_b32_e32 v1, 7, v13
	s_movk_i32 s13, 0xf0
	s_addc_u32 s49, s55, s7
	v_lshl_or_b32 v176, v4, 11, v2
	v_and_or_b32 v4, v1, s13, v12
	s_movk_i32 s13, 0xe0
	s_lshl_b32 s12, s12, 8
	s_lshr_b32 s7, s3, 6
	v_and_or_b32 v1, v1, s13, v3
	s_ashr_i32 s13, s12, 31
	s_lshr_b32 s6, s3, 8
	s_lshl_b32 s64, s7, 10
	s_and_b32 s20, s3, 0x3fffffc0
	s_and_b32 s18, s3, 0xc0
	s_lshl_b64 s[12:13], s[12:13], 2
	s_add_u32 s12, s4, s12
	v_lshl_or_b32 v180, v1, 11, v2
	v_or_b32_e32 v1, s18, v242
	s_addc_u32 s13, s5, s13
	s_bfe_u32 s4, s3, 0x10007
	v_lshlrev_b32_e32 v171, 2, v1
	s_mulk_i32 s4, 0xb00
	s_lshl_b32 s5, s46, 7
	v_mov_b32_e32 v1, 0x7f
	s_add_i32 s5, s5, s4
	v_bitop3_b32 v15, s18, v1, v242 bitop3:0xc8
	v_and_b32_e32 v6, 15, v5
	v_bfe_u32 v7, v5, 4, 2
	v_and_b32_e32 v5, 64, v5
	v_lshl_or_b32 v6, v6, 2, v7
	v_or_b32_e32 v5, v5, v6
	v_and_b32_e32 v6, 15, v4
	v_bfe_u32 v7, v4, 4, 2
	v_and_b32_e32 v4, 64, v4
	v_lshl_or_b32 v6, v6, 2, v7
	v_or_b32_e32 v4, v4, v6
	v_lshl_or_b32 v174, v5, 11, v2
	v_lshl_or_b32 v178, v4, 11, v2
	v_or_b32_e32 v2, s5, v15
	v_ashrrev_i32_e32 v3, 31, v2
	v_lshlrev_b64 v[2:3], 2, v[2:3]
	v_lshl_add_u64 v[4:5], s[0:1], 0, v[2:3]
	s_mul_i32 s1, s6, 0x5800
	s_mul_hi_u32 s0, s6, 0x5800
	s_add_u32 s18, s60, s1
	s_addc_u32 s19, s61, s0
	s_lshl_b32 s0, s20, 2
	s_add_i32 s0, s0, 0
	s_add_i32 s65, s0, 0x22100
	v_lshl_add_u64 v[2:3], s[18:19], 0, v[2:3]
	s_mov_b32 m0, s65
	s_add_i32 s70, s64, 0
	global_load_lds_dword v[2:3], off
	s_add_i32 m0, s0, 0x22900
	v_writelane_b32 v255, s91, 11
	global_load_lds_dword v[4:5], off
	s_add_i32 m0, s0, 0x23100
	v_mov_b32_e32 v183, 0
	global_load_lds_dword v171, s[12:13]
	s_add_i32 m0, s70, 0x10000
	v_writelane_b32 v255, s96, 12
	global_load_lds_dwordx4 v176, s[48:49]
	s_add_i32 m0, s70, 0x12000
	s_add_u32 s0, s48, 0x40000
	global_load_lds_dwordx4 v180, s[48:49]
	s_addc_u32 s1, s49, 0
	s_add_i32 m0, s70, 0x14000
	s_add_i32 s71, s70, 0x2000
	global_load_lds_dwordx4 v176, s[0:1]
	s_add_i32 m0, s70, 0x16000
	v_mov_b32_e32 v177, v183
	global_load_lds_dwordx4 v180, s[0:1]
	s_mov_b32 m0, s70
	s_add_u32 s0, s8, 0x40000
	global_load_lds_dwordx4 v174, s[8:9]
	s_mov_b32 m0, s71
	s_addc_u32 s1, s9, 0
	s_add_i32 s74, s70, 0x4000
	global_load_lds_dwordx4 v178, s[8:9]
	s_mov_b32 m0, s74
	s_add_i32 s75, s70, 0x6000
	global_load_lds_dwordx4 v174, s[0:1]
	s_mov_b32 m0, s75
	v_mov_b32_e32 v181, v183
	global_load_lds_dwordx4 v178, s[0:1]
	v_mov_b32_e32 v175, v183
	v_mov_b32_e32 v179, v183
	s_cmp_eq_u32 s6, 1
	v_writelane_b32 v255, s97, 13
	s_movk_i32 s76, 0x5800
	s_mov_b32 s29, 0
	v_lshl_add_u64 v[8:9], s[48:49], 0, v[176:177]
	v_lshl_add_u64 v[6:7], s[48:49], 0, v[180:181]
	v_lshl_add_u64 v[2:3], s[8:9], 0, v[174:175]
	s_cselect_b64 s[20:21], -1, 0
	s_cmp_lg_u32 s6, 1
	v_lshl_add_u64 v[4:5], s[8:9], 0, v[178:179]
	s_cbranch_scc1 .LBB0_551
	s_barrier
.LBB0_551:
	s_add_u32 s22, s88, 0x2a00000
	s_addc_u32 s23, s89, 0
	s_add_u32 s24, s88, 0x2d00000
	s_addc_u32 s25, s89, 0
	s_lshl_b32 s0, s7, 5
	s_mov_b64 s[26:27], 0x80
	s_and_b32 s7, s0, 0x60
	s_add_i32 m0, s70, 0x18000
	v_lshl_add_u64 v[8:9], v[8:9], 0, s[26:27]
	s_lshl_b32 s5, s6, 13
	s_lshl_b32 s12, s7, 7
	s_waitcnt vmcnt(2)
	s_barrier
	global_load_lds_dwordx4 v[8:9], off
	v_lshl_add_u64 v[6:7], v[6:7], 0, s[26:27]
	s_add_i32 m0, s70, 0x1a000
	s_add_i32 s77, s70, 0x8000
	s_add_i32 s78, s70, 0xa000
	global_load_lds_dwordx4 v[6:7], off
	v_lshl_add_u64 v[2:3], v[2:3], 0, s[26:27]
	s_mov_b32 m0, s77
	s_add_u32 s0, s48, 0x40080
	global_load_lds_dwordx4 v[2:3], off
	v_lshl_add_u64 v[2:3], v[4:5], 0, s[26:27]
	s_mov_b32 m0, s78
	s_addc_u32 s1, s49, 0
	global_load_lds_dwordx4 v[2:3], off
	s_add_i32 m0, s70, 0x1c000
	v_lshl_add_u64 v[2:3], s[0:1], 0, v[176:177]
	global_load_lds_dwordx4 v[2:3], off
	v_lshl_add_u64 v[2:3], s[0:1], 0, v[180:181]
	s_add_i32 m0, s70, 0x1e000
	v_and_b32_e32 v173, 15, v170
	global_load_lds_dwordx4 v[2:3], off
	v_lshlrev_b32_e32 v1, 1, v14
	v_lshlrev_b32_e32 v4, 6, v170
	s_movk_i32 s0, 0x3c0
	v_lshl_or_b32 v2, v173, 6, v1
	v_and_b32_e32 v3, 32, v172
	v_and_or_b32 v1, v4, s0, v1
	v_lshl_or_b32 v185, s6, 6, v173
	v_bitop3_b32 v210, s12, v1, v3 bitop3:0xf6
	s_lshl_b32 s6, s6, 9
	v_lshlrev_b32_e32 v1, 8, v173
	v_bitop3_b32 v2, v2, s5, v3 bitop3:0xde
	v_or_b32_e32 v184, s7, v14
	v_add_u32_e32 v3, s6, v1
	s_and_b32 s79, s3, 0xffffff00
	v_or_b32_e32 v3, v3, v184
	v_lshlrev_b32_e32 v3, 2, v3
	v_or_b32_e32 v1, v184, v1
	s_cmpk_gt_u32 s3, 0xff
	v_or_b32_e32 v211, s4, v15
	v_add_u32_e32 v212, 0xffffc800, v3
	v_add_u32_e32 v213, 0xffffd800, v3
	v_or_b32_e32 v3, 0xfffff000, v1
	s_cselect_b64 s[4:5], -1, 0
	s_add_i32 s3, s6, 0x400
	v_or_b32_e32 v1, 0xfffff004, v1
	v_add_lshl_u32 v217, v1, s6, 2
	v_add_lshl_u32 v218, v1, s3, 2
	v_lshlrev_b32_e32 v1, 8, v170
	v_add_lshl_u32 v215, v3, s6, 2
	v_add_lshl_u32 v216, v3, s3, 2
	v_and_b32_e32 v1, 0x38000, v1
	v_lshlrev_b32_e32 v3, 11, v12
	v_cmp_lt_u32_e64 s[0:1], 13, v173
	v_cmp_gt_u32_e32 vcc, 2, v173
	v_or3_b32 v1, v10, v1, v3
	s_and_b64 s[30:31], s[0:1], s[4:5]
	s_and_b64 s[34:35], s[14:15], vcc
	s_ashr_i32 s6, s33, 31
	s_ashr_i32 s92, s2, 31
	v_mov_b32_e32 v186, v174
	v_lshlrev_b32_e32 v1, 4, v13
	s_waitcnt vmcnt(6)
	s_add_u32 s36, s60, 0xb000
	v_and_b32_e32 v1, 0x78000, v1
	s_addc_u32 s37, s61, 0
	v_or3_b32 v1, v10, v1, v3
	s_add_i32 s93, 0, 0x10000
	s_add_i32 s90, 0, 0x14000
	v_add_u32_e32 v214, -14, v173
	v_mov_b32_e32 v187, v183
	v_mov_b32_e32 v188, v178
	v_mov_b32_e32 v189, v183
	v_mov_b64_e32 v[190:191], 0x580
	v_mov_b64_e32 v[192:193], 0x57f
	v_add_u32_e32 v219, s93, v210
	v_add_u32_e32 v220, s90, v210
	v_add_u32_e32 v221, 0, v2
	v_mov_b32_e32 v222, 0x358637bd
	s_add_i32 s91, 0, 0x20000
	s_add_i32 s97, 0, 0x20010
	s_add_i32 s96, 0, 0x20200
	s_add_i32 s87, 0, 0x20210
	s_movk_i32 s12, 0x1600
	v_lshlrev_b32_e32 v182, 1, v184
	s_barrier
	s_branch .LBB0_554

.LBB0_560:
	s_mov_b32 s98, 1.0
	s_mov_b32 s99, 1.0
	s_mov_b32 s100, 0xbfb8aa3b
	s_mov_b32 s101, 0xbfb8aa3b
	v_readfirstlane_b32 s50, v170
	v_and_b32_e32 v224, 15, v170
	v_bfe_u32 v245, v170, 4, 2
	s_lshr_b32 s50, s50, 6
	s_and_b32 s51, s50, 3
	s_lshr_b32 s50, s50, 2
	s_lshl_b32 s51, s51, 7
	v_lshl_add_u32 v225, v245, 5, s51
	s_bitcmp1_b32 s29, 0
	s_cselect_b32 s3, 0x1800, 0
	s_add_i32 s3, s3, 0x22100
	v_add_u32_e32 v226, s3, v225
	s_lshl_b32 s51, s50, 8
	s_add_i32 s51, s51, s3
	v_lshl_add_u32 v245, v224, 4, s51
	ds_read_b128 v[146:149], v245 offset:4096
	ds_read_b128 v[150:153], v245 offset:4608
	ds_read_b128 v[154:157], v226 offset:5120
	ds_read_b128 v[158:161], v226 offset:5136
	ds_read_b128 v[162:165], v226 offset:5632
	ds_read_b128 v[166:169], v226 offset:5648
	s_lshl_b32 s51, s50, 11
	s_add_i32 s51, s51, 0x1f800
	v_add_u32_e32 v227, s51, v225
	s_mul_i32 s51, s28, 0xb000
	s_lshl_b32 s3, s46, 9
	s_add_i32 s51, s51, s3
	v_add_u32_e32 v228, s51, v225
	v_add_u32_e32 v229, 0x2c00, v228
	v_add_u32_e32 v230, 0x5800, v228
	v_add_u32_e32 v231, 0x8400, v228
	s_lshl_b32 s51, s28, 8
	s_lshl_b32 s3, s50, 6
	s_add_i32 s51, s51, s3
	v_lshl_add_u32 v244, v224, 2, s51
	v_mul_u32_u24_e32 v244, 0x1600, v244
	s_lshl_b32 s3, s46, 8
	v_lshrrev_b32_e32 v245, 1, v225
	v_add3_u32 v244, v244, v245, s3
	v_mov_b32_e32 v245, 0x358637bd
	s_waitcnt lgkmcnt(4)
	v_fmamk_f32 v146, v146, 0x3a800000, v245
	v_fmamk_f32 v147, v147, 0x3a800000, v245
	v_fmamk_f32 v148, v148, 0x3a800000, v245
	v_fmamk_f32 v149, v149, 0x3a800000, v245
	v_fmamk_f32 v150, v150, 0x3a800000, v245
	v_fmamk_f32 v151, v151, 0x3a800000, v245
	v_fmamk_f32 v152, v152, 0x3a800000, v245
	v_fmamk_f32 v153, v153, 0x3a800000, v245
	v_rsq_f32_e32 v146, v146
	v_rsq_f32_e32 v147, v147
	v_rsq_f32_e32 v148, v148
	v_rsq_f32_e32 v149, v149
	v_rsq_f32_e32 v150, v150
	v_rsq_f32_e32 v151, v151
	v_rsq_f32_e32 v152, v152
	v_rsq_f32_e32 v153, v153
	s_waitcnt lgkmcnt(0)
	v_pk_fma_f32 v[62:63], v[62:63], v[146:147], v[154:155] op_sel:[0,0,0] op_sel_hi:[1,0,1]
	v_pk_fma_f32 v[64:65], v[64:65], v[146:147], v[156:157] op_sel:[0,0,0] op_sel_hi:[1,0,1]
	v_pk_fma_f32 v[42:43], v[42:43], v[146:147], v[158:159] op_sel:[0,0,0] op_sel_hi:[1,0,1]
	v_pk_fma_f32 v[44:45], v[44:45], v[146:147], v[160:161] op_sel:[0,0,0] op_sel_hi:[1,0,1]
	v_pk_fma_f32 v[134:135], v[134:135], v[146:147], v[162:163] op_sel:[0,0,0] op_sel_hi:[1,0,1]
	v_pk_fma_f32 v[136:137], v[136:137], v[146:147], v[164:165] op_sel:[0,0,0] op_sel_hi:[1,0,1]
	v_pk_fma_f32 v[74:75], v[74:75], v[146:147], v[166:167] op_sel:[0,0,0] op_sel_hi:[1,0,1]
	v_pk_fma_f32 v[76:77], v[76:77], v[146:147], v[168:169] op_sel:[0,0,0] op_sel_hi:[1,0,1]
	v_pk_fma_f32 v[50:51], v[50:51], v[146:147], v[154:155] op_sel:[0,1,0] op_sel_hi:[1,1,1]
	v_pk_fma_f32 v[52:53], v[52:53], v[146:147], v[156:157] op_sel:[0,1,0] op_sel_hi:[1,1,1]
	v_pk_fma_f32 v[38:39], v[38:39], v[146:147], v[158:159] op_sel:[0,1,0] op_sel_hi:[1,1,1]
	v_pk_fma_f32 v[40:41], v[40:41], v[146:147], v[160:161] op_sel:[0,1,0] op_sel_hi:[1,1,1]
	v_pk_fma_f32 v[130:131], v[130:131], v[146:147], v[162:163] op_sel:[0,1,0] op_sel_hi:[1,1,1]
	v_pk_fma_f32 v[132:133], v[132:133], v[146:147], v[164:165] op_sel:[0,1,0] op_sel_hi:[1,1,1]
	v_pk_fma_f32 v[70:71], v[70:71], v[146:147], v[166:167] op_sel:[0,1,0] op_sel_hi:[1,1,1]
	v_pk_fma_f32 v[72:73], v[72:73], v[146:147], v[168:169] op_sel:[0,1,0] op_sel_hi:[1,1,1]
	v_pk_fma_f32 v[46:47], v[46:47], v[148:149], v[154:155] op_sel:[0,0,0] op_sel_hi:[1,0,1]
	v_pk_fma_f32 v[48:49], v[48:49], v[148:149], v[156:157] op_sel:[0,0,0] op_sel_hi:[1,0,1]
	v_pk_fma_f32 v[34:35], v[34:35], v[148:149], v[158:159] op_sel:[0,0,0] op_sel_hi:[1,0,1]
	v_pk_fma_f32 v[36:37], v[36:37], v[148:149], v[160:161] op_sel:[0,0,0] op_sel_hi:[1,0,1]
	v_pk_fma_f32 v[78:79], v[78:79], v[148:149], v[162:163] op_sel:[0,0,0] op_sel_hi:[1,0,1]
	v_pk_fma_f32 v[80:81], v[80:81], v[148:149], v[164:165] op_sel:[0,0,0] op_sel_hi:[1,0,1]
	v_pk_fma_f32 v[66:67], v[66:67], v[148:149], v[166:167] op_sel:[0,0,0] op_sel_hi:[1,0,1]
	v_pk_fma_f32 v[68:69], v[68:69], v[148:149], v[168:169] op_sel:[0,0,0] op_sel_hi:[1,0,1]
	v_pk_fma_f32 v[142:143], v[142:143], v[148:149], v[154:155] op_sel:[0,1,0] op_sel_hi:[1,1,1]
	v_pk_fma_f32 v[144:145], v[144:145], v[148:149], v[156:157] op_sel:[0,1,0] op_sel_hi:[1,1,1]
	v_pk_fma_f32 v[82:83], v[82:83], v[148:149], v[158:159] op_sel:[0,1,0] op_sel_hi:[1,1,1]
	v_pk_fma_f32 v[84:85], v[84:85], v[148:149], v[160:161] op_sel:[0,1,0] op_sel_hi:[1,1,1]
	v_pk_fma_f32 v[138:139], v[138:139], v[148:149], v[162:163] op_sel:[0,1,0] op_sel_hi:[1,1,1]
	v_pk_fma_f32 v[140:141], v[140:141], v[148:149], v[164:165] op_sel:[0,1,0] op_sel_hi:[1,1,1]
	v_pk_fma_f32 v[98:99], v[98:99], v[148:149], v[166:167] op_sel:[0,1,0] op_sel_hi:[1,1,1]
	v_pk_fma_f32 v[100:101], v[100:101], v[148:149], v[168:169] op_sel:[0,1,0] op_sel_hi:[1,1,1]
	v_pk_fma_f32 v[94:95], v[94:95], v[150:151], v[154:155] op_sel:[0,0,0] op_sel_hi:[1,0,1]
	v_pk_fma_f32 v[96:97], v[96:97], v[150:151], v[156:157] op_sel:[0,0,0] op_sel_hi:[1,0,1]
	v_pk_fma_f32 v[10:11], v[10:11], v[150:151], v[158:159] op_sel:[0,0,0] op_sel_hi:[1,0,1]
	v_pk_fma_f32 v[12:13], v[12:13], v[150:151], v[160:161] op_sel:[0,0,0] op_sel_hi:[1,0,1]
	v_pk_fma_f32 v[110:111], v[110:111], v[150:151], v[162:163] op_sel:[0,0,0] op_sel_hi:[1,0,1]
	v_pk_fma_f32 v[112:113], v[112:113], v[150:151], v[164:165] op_sel:[0,0,0] op_sel_hi:[1,0,1]
	v_pk_fma_f32 v[22:23], v[22:23], v[150:151], v[166:167] op_sel:[0,0,0] op_sel_hi:[1,0,1]
	v_pk_fma_f32 v[24:25], v[24:25], v[150:151], v[168:169] op_sel:[0,0,0] op_sel_hi:[1,0,1]
	v_pk_fma_f32 v[90:91], v[90:91], v[150:151], v[154:155] op_sel:[0,1,0] op_sel_hi:[1,1,1]
	v_pk_fma_f32 v[92:93], v[92:93], v[150:151], v[156:157] op_sel:[0,1,0] op_sel_hi:[1,1,1]
	v_pk_fma_f32 v[6:7], v[6:7], v[150:151], v[158:159] op_sel:[0,1,0] op_sel_hi:[1,1,1]
	v_pk_fma_f32 v[8:9], v[8:9], v[150:151], v[160:161] op_sel:[0,1,0] op_sel_hi:[1,1,1]
	v_pk_fma_f32 v[106:107], v[106:107], v[150:151], v[162:163] op_sel:[0,1,0] op_sel_hi:[1,1,1]
	v_pk_fma_f32 v[108:109], v[108:109], v[150:151], v[164:165] op_sel:[0,1,0] op_sel_hi:[1,1,1]
	v_pk_fma_f32 v[18:19], v[18:19], v[150:151], v[166:167] op_sel:[0,1,0] op_sel_hi:[1,1,1]
	v_pk_fma_f32 v[20:21], v[20:21], v[150:151], v[168:169] op_sel:[0,1,0] op_sel_hi:[1,1,1]
	v_pk_fma_f32 v[86:87], v[86:87], v[152:153], v[154:155] op_sel:[0,0,0] op_sel_hi:[1,0,1]
	v_pk_fma_f32 v[88:89], v[88:89], v[152:153], v[156:157] op_sel:[0,0,0] op_sel_hi:[1,0,1]
	v_pk_fma_f32 v[2:3], v[2:3], v[152:153], v[158:159] op_sel:[0,0,0] op_sel_hi:[1,0,1]
	v_pk_fma_f32 v[4:5], v[4:5], v[152:153], v[160:161] op_sel:[0,0,0] op_sel_hi:[1,0,1]
	v_pk_fma_f32 v[102:103], v[102:103], v[152:153], v[162:163] op_sel:[0,0,0] op_sel_hi:[1,0,1]
	v_pk_fma_f32 v[104:105], v[104:105], v[152:153], v[164:165] op_sel:[0,0,0] op_sel_hi:[1,0,1]
	v_pk_fma_f32 v[14:15], v[14:15], v[152:153], v[166:167] op_sel:[0,0,0] op_sel_hi:[1,0,1]
	v_pk_fma_f32 v[16:17], v[16:17], v[152:153], v[168:169] op_sel:[0,0,0] op_sel_hi:[1,0,1]
	v_pk_fma_f32 v[114:115], v[114:115], v[152:153], v[154:155] op_sel:[0,1,0] op_sel_hi:[1,1,1]
	v_pk_fma_f32 v[116:117], v[116:117], v[152:153], v[156:157] op_sel:[0,1,0] op_sel_hi:[1,1,1]
	v_pk_fma_f32 v[26:27], v[26:27], v[152:153], v[158:159] op_sel:[0,1,0] op_sel_hi:[1,1,1]
	v_pk_fma_f32 v[28:29], v[28:29], v[152:153], v[160:161] op_sel:[0,1,0] op_sel_hi:[1,1,1]
	v_pk_fma_f32 v[126:127], v[126:127], v[152:153], v[162:163] op_sel:[0,1,0] op_sel_hi:[1,1,1]
	v_pk_fma_f32 v[128:129], v[128:129], v[152:153], v[164:165] op_sel:[0,1,0] op_sel_hi:[1,1,1]
	v_pk_fma_f32 v[58:59], v[58:59], v[152:153], v[166:167] op_sel:[0,1,0] op_sel_hi:[1,1,1]
	v_pk_fma_f32 v[60:61], v[60:61], v[152:153], v[168:169] op_sel:[0,1,0] op_sel_hi:[1,1,1]
	v_cmp_eq_u32_e32 vcc, 15, v224
	s_and_saveexec_b64 s[8:9], vcc
	ds_write_b128 v227, v[46:49] offset:2048
	ds_write_b128 v227, v[34:37] offset:2064
	ds_write_b128 v227, v[78:81] offset:2560
	ds_write_b128 v227, v[66:69] offset:2576
	ds_write_b128 v227, v[142:145] offset:3072
	ds_write_b128 v227, v[82:85] offset:3088
	ds_write_b128 v227, v[138:141] offset:3584
	ds_write_b128 v227, v[98:101] offset:3600
	ds_write_b128 v227, v[86:89] offset:6144
	ds_write_b128 v227, v[2:5] offset:6160
	ds_write_b128 v227, v[102:105] offset:6656
	ds_write_b128 v227, v[14:17] offset:6672
	ds_write_b128 v227, v[114:117] offset:7168
	ds_write_b128 v227, v[26:29] offset:7184
	ds_write_b128 v227, v[126:129] offset:7680
	ds_write_b128 v227, v[58:61] offset:7696
	s_cmp_lg_u32 s50, 1
	s_cbranch_scc1 .Lnepia_nohalo
	s_add_u32 s48, s88, 0x2a00000
	s_addc_u32 s49, s89, 0
	global_store_dwordx4 v228, v[86:89], s[48:49] offset:0
	global_store_dwordx4 v228, v[2:5], s[48:49] offset:16
	global_store_dwordx4 v229, v[102:105], s[48:49] offset:0
	global_store_dwordx4 v229, v[14:17], s[48:49] offset:16
	global_store_dwordx4 v230, v[114:117], s[48:49] offset:0
	global_store_dwordx4 v230, v[26:29], s[48:49] offset:16
	global_store_dwordx4 v231, v[126:129], s[48:49] offset:0
	global_store_dwordx4 v231, v[58:61], s[48:49] offset:16
.Lnepia_nohalo:
	s_or_b64 exec, exec, s[8:9]
	s_waitcnt lgkmcnt(0)
	s_barrier
	ds_read_b128 v[194:197], v226 offset:512
	ds_read_b128 v[198:201], v226 offset:1536
	ds_read_b128 v[202:205], v226 offset:2560
	ds_read_b128 v[206:209], v226 offset:3584
	s_cmp_eq_u32 s50, 0
	s_cbranch_scc1 .Lnepia_z0
	ds_read_b128 v[118:121], v227 offset:512
	ds_read_b128 v[122:125], v227 offset:1536
	s_branch .Lnepia_j0
.Lnepia_z0:
	v_mov_b32_e32 v118, 0
	v_mov_b32_e32 v122, 0
	v_mov_b32_e32 v119, 0
	v_mov_b32_e32 v123, 0
	v_mov_b32_e32 v120, 0
	v_mov_b32_e32 v124, 0
	v_mov_b32_e32 v121, 0
	v_mov_b32_e32 v125, 0
.Lnepia_j0:
	s_waitcnt lgkmcnt(0)
	ds_read_b128 v[146:149], v226 offset:0
	ds_read_b128 v[150:153], v226 offset:1024
	ds_read_b128 v[154:157], v226 offset:2048
	ds_read_b128 v[158:161], v226 offset:3072
	s_cmp_eq_u32 s50, 0
	s_cbranch_scc1 .Lnepia_z1
	ds_read_b128 v[162:165], v227 offset:0
	ds_read_b128 v[166:169], v227 offset:1024
	s_branch .Lnepia_j1
.Lnepia_z1:
	v_mov_b32_e32 v162, 0
	v_mov_b32_e32 v166, 0
	v_mov_b32_e32 v163, 0
	v_mov_b32_e32 v167, 0
	v_mov_b32_e32 v164, 0
	v_mov_b32_e32 v168, 0
	v_mov_b32_e32 v165, 0
	v_mov_b32_e32 v169, 0
.Lnepia_j1:
	v_mov_b32_dpp v118, v78 row_shr:1 row_mask:0xf bank_mask:0xf
	v_mov_b32_dpp v122, v138 row_shr:1 row_mask:0xf bank_mask:0xf
	v_mov_b32_dpp v119, v79 row_shr:1 row_mask:0xf bank_mask:0xf
	v_mov_b32_dpp v123, v139 row_shr:1 row_mask:0xf bank_mask:0xf
	v_mov_b32_dpp v120, v80 row_shr:1 row_mask:0xf bank_mask:0xf
	v_mov_b32_dpp v124, v140 row_shr:1 row_mask:0xf bank_mask:0xf
	v_mov_b32_dpp v121, v81 row_shr:1 row_mask:0xf bank_mask:0xf
	v_mov_b32_dpp v125, v141 row_shr:1 row_mask:0xf bank_mask:0xf
	v_pk_fma_f32 v[138:139], v[202:203], v[138:139], v[206:207]
	v_pk_fma_f32 v[140:141], v[204:205], v[140:141], v[208:209]
	v_pk_fma_f32 v[138:139], v[198:199], v[78:79], v[138:139]
	v_pk_fma_f32 v[140:141], v[200:201], v[80:81], v[140:141]
	v_pk_fma_f32 v[138:139], v[194:195], v[130:131], v[138:139]
	v_pk_fma_f32 v[140:141], v[196:197], v[132:133], v[140:141]
	v_pk_fma_f32 v[78:79], v[202:203], v[78:79], v[206:207]
	v_pk_fma_f32 v[80:81], v[204:205], v[80:81], v[208:209]
	v_pk_fma_f32 v[78:79], v[198:199], v[130:131], v[78:79]
	v_pk_fma_f32 v[80:81], v[200:201], v[132:133], v[80:81]
	v_pk_fma_f32 v[78:79], v[194:195], v[134:135], v[78:79]
	v_pk_fma_f32 v[80:81], v[196:197], v[136:137], v[80:81]
	v_pk_fma_f32 v[130:131], v[202:203], v[130:131], v[206:207]
	v_pk_fma_f32 v[132:133], v[204:205], v[132:133], v[208:209]
	v_pk_fma_f32 v[130:131], v[198:199], v[134:135], v[130:131]
	v_pk_fma_f32 v[132:133], v[200:201], v[136:137], v[132:133]
	v_pk_fma_f32 v[130:131], v[194:195], v[122:123], v[130:131]
	v_pk_fma_f32 v[132:133], v[196:197], v[124:125], v[132:133]
	v_pk_fma_f32 v[134:135], v[202:203], v[134:135], v[206:207]
	v_pk_fma_f32 v[136:137], v[204:205], v[136:137], v[208:209]
	v_pk_fma_f32 v[134:135], v[198:199], v[122:123], v[134:135]
	v_pk_fma_f32 v[136:137], v[200:201], v[124:125], v[136:137]
	v_pk_fma_f32 v[134:135], v[194:195], v[118:119], v[134:135]
	v_pk_fma_f32 v[136:137], v[196:197], v[120:121], v[136:137]
	s_cmp_lg_u32 s50, 0
	s_cbranch_scc1 .Lnepia_np0
	v_cmp_eq_u32_e32 vcc, 0, v224
	s_and_saveexec_b64 s[8:9], vcc
	s_add_u32 s48, s88, 0x2d00000
	s_addc_u32 s49, s89, 0
	global_store_dwordx4 v229, v[134:137], s[48:49] offset:0
	global_store_dwordx4 v231, v[130:133], s[48:49] offset:0
	s_or_b64 exec, exec, s[8:9]
	s_nop 1
.Lnepia_np0:
	s_waitcnt lgkmcnt(0)
	ds_read_b128 v[194:197], v226 offset:528
	ds_read_b128 v[198:201], v226 offset:1552
	ds_read_b128 v[202:205], v226 offset:2576
	ds_read_b128 v[206:209], v226 offset:3600
	s_cmp_eq_u32 s50, 0
	s_cbranch_scc1 .Lnepia_z2
	ds_read_b128 v[118:121], v227 offset:528
	ds_read_b128 v[122:125], v227 offset:1552
	s_branch .Lnepia_j2

.Lnepia_j2:
	v_mov_b32_dpp v162, v46 row_shr:1 row_mask:0xf bank_mask:0xf
	v_mov_b32_dpp v166, v142 row_shr:1 row_mask:0xf bank_mask:0xf
	v_mov_b32_dpp v163, v47 row_shr:1 row_mask:0xf bank_mask:0xf
	v_mov_b32_dpp v167, v143 row_shr:1 row_mask:0xf bank_mask:0xf
	v_mov_b32_dpp v164, v48 row_shr:1 row_mask:0xf bank_mask:0xf
	v_mov_b32_dpp v168, v144 row_shr:1 row_mask:0xf bank_mask:0xf
	v_mov_b32_dpp v165, v49 row_shr:1 row_mask:0xf bank_mask:0xf
	v_mov_b32_dpp v169, v145 row_shr:1 row_mask:0xf bank_mask:0xf
	v_pk_fma_f32 v[142:143], v[154:155], v[142:143], v[158:159]
	v_pk_fma_f32 v[144:145], v[156:157], v[144:145], v[160:161]
	v_pk_fma_f32 v[142:143], v[150:151], v[46:47], v[142:143]
	v_pk_fma_f32 v[144:145], v[152:153], v[48:49], v[144:145]
	v_pk_fma_f32 v[142:143], v[146:147], v[50:51], v[142:143]
	v_pk_fma_f32 v[144:145], v[148:149], v[52:53], v[144:145]
	v_pk_fma_f32 v[46:47], v[154:155], v[46:47], v[158:159]
	v_pk_fma_f32 v[48:49], v[156:157], v[48:49], v[160:161]
	v_pk_fma_f32 v[46:47], v[150:151], v[50:51], v[46:47]
	v_pk_fma_f32 v[48:49], v[152:153], v[52:53], v[48:49]
	v_pk_fma_f32 v[46:47], v[146:147], v[62:63], v[46:47]
	v_pk_fma_f32 v[48:49], v[148:149], v[64:65], v[48:49]
	v_pk_fma_f32 v[50:51], v[154:155], v[50:51], v[158:159]
	v_pk_fma_f32 v[52:53], v[156:157], v[52:53], v[160:161]
	v_pk_fma_f32 v[50:51], v[150:151], v[62:63], v[50:51]
	v_pk_fma_f32 v[52:53], v[152:153], v[64:65], v[52:53]
	v_pk_fma_f32 v[50:51], v[146:147], v[166:167], v[50:51]
	v_pk_fma_f32 v[52:53], v[148:149], v[168:169], v[52:53]
	v_pk_fma_f32 v[62:63], v[154:155], v[62:63], v[158:159]
	v_pk_fma_f32 v[64:65], v[156:157], v[64:65], v[160:161]
	v_pk_fma_f32 v[62:63], v[150:151], v[166:167], v[62:63]
	v_pk_fma_f32 v[64:65], v[152:153], v[168:169], v[64:65]
	v_pk_fma_f32 v[62:63], v[146:147], v[162:163], v[62:63]
	v_pk_fma_f32 v[64:65], v[148:149], v[164:165], v[64:65]
	s_cmp_lg_u32 s50, 0
	s_cbranch_scc1 .Lnepia_np1
	v_cmp_eq_u32_e32 vcc, 0, v224
	s_and_saveexec_b64 s[8:9], vcc
	s_add_u32 s48, s88, 0x2d00000
	s_addc_u32 s49, s89, 0
	global_store_dwordx4 v228, v[62:65], s[48:49] offset:0
	global_store_dwordx4 v230, v[50:53], s[48:49] offset:0
	s_or_b64 exec, exec, s[8:9]
	s_nop 1
.Lnepia_np1:
	v_pk_mul_f32 v[30:31], v[62:63], s[100:101]
	v_pk_mul_f32 v[32:33], v[64:65], s[100:101]
	v_pk_mul_f32 v[54:55], v[50:51], s[100:101]
	v_pk_mul_f32 v[56:57], v[52:53], s[100:101]
	v_exp_f32_e32 v30, v30
	v_exp_f32_e32 v31, v31
	v_exp_f32_e32 v32, v32
	v_exp_f32_e32 v33, v33
	v_exp_f32_e32 v54, v54
	v_exp_f32_e32 v55, v55
	v_exp_f32_e32 v56, v56
	v_exp_f32_e32 v57, v57
	v_pk_add_f32 v[30:31], v[30:31], s[98:99]
	v_pk_add_f32 v[32:33], v[32:33], s[98:99]
	v_pk_add_f32 v[54:55], v[54:55], s[98:99]
	v_pk_add_f32 v[56:57], v[56:57], s[98:99]
	v_rcp_f32_e32 v30, v30
	v_rcp_f32_e32 v31, v31
	v_rcp_f32_e32 v32, v32
	v_rcp_f32_e32 v33, v33
	v_rcp_f32_e32 v54, v54
	v_rcp_f32_e32 v55, v55
	v_rcp_f32_e32 v56, v56
	v_rcp_f32_e32 v57, v57
	v_pk_mul_f32 v[62:63], v[62:63], v[134:135]
	v_pk_mul_f32 v[64:65], v[64:65], v[136:137]
	v_pk_mul_f32 v[50:51], v[50:51], v[130:131]
	v_pk_mul_f32 v[52:53], v[52:53], v[132:133]
	v_pk_mul_f32 v[62:63], v[62:63], v[30:31]
	v_pk_mul_f32 v[64:65], v[64:65], v[32:33]
	v_pk_mul_f32 v[50:51], v[50:51], v[54:55]
	v_pk_mul_f32 v[52:53], v[52:53], v[56:57]
	v_pk_mul_f32 v[30:31], v[46:47], s[100:101]
	v_pk_mul_f32 v[32:33], v[48:49], s[100:101]
	v_pk_mul_f32 v[54:55], v[142:143], s[100:101]
	v_pk_mul_f32 v[56:57], v[144:145], s[100:101]
	v_exp_f32_e32 v30, v30
	v_exp_f32_e32 v31, v31
	v_exp_f32_e32 v32, v32
	v_exp_f32_e32 v33, v33
	v_exp_f32_e32 v54, v54
	v_exp_f32_e32 v55, v55
	v_exp_f32_e32 v56, v56
	v_exp_f32_e32 v57, v57
	v_pk_add_f32 v[30:31], v[30:31], s[98:99]
	v_pk_add_f32 v[32:33], v[32:33], s[98:99]
	v_pk_add_f32 v[54:55], v[54:55], s[98:99]
	v_pk_add_f32 v[56:57], v[56:57], s[98:99]
	v_rcp_f32_e32 v30, v30
	v_rcp_f32_e32 v31, v31
	v_rcp_f32_e32 v32, v32
	v_rcp_f32_e32 v33, v33
	v_rcp_f32_e32 v54, v54
	v_rcp_f32_e32 v55, v55
	v_rcp_f32_e32 v56, v56
	v_rcp_f32_e32 v57, v57
	v_pk_mul_f32 v[46:47], v[46:47], v[78:79]
	v_pk_mul_f32 v[48:49], v[48:49], v[80:81]
	v_pk_mul_f32 v[142:143], v[142:143], v[138:139]
	v_pk_mul_f32 v[144:145], v[144:145], v[140:141]
	v_pk_mul_f32 v[46:47], v[46:47], v[30:31]
	v_pk_mul_f32 v[48:49], v[48:49], v[32:33]
	v_pk_mul_f32 v[142:143], v[142:143], v[54:55]
	v_pk_mul_f32 v[144:145], v[144:145], v[56:57]
	s_waitcnt lgkmcnt(0)
	ds_read_b128 v[146:149], v226 offset:16
	ds_read_b128 v[150:153], v226 offset:1040
	ds_read_b128 v[154:157], v226 offset:2064
	ds_read_b128 v[158:161], v226 offset:3088
	s_cmp_eq_u32 s50, 0
	s_cbranch_scc1 .Lnepia_z3
	ds_read_b128 v[162:165], v227 offset:16
	ds_read_b128 v[166:169], v227 offset:1040
	s_branch .Lnepia_j3

.Lnepia_j3:
	v_mov_b32_dpp v118, v66 row_shr:1 row_mask:0xf bank_mask:0xf
	v_mov_b32_dpp v122, v98 row_shr:1 row_mask:0xf bank_mask:0xf
	v_mov_b32_dpp v119, v67 row_shr:1 row_mask:0xf bank_mask:0xf
	v_mov_b32_dpp v123, v99 row_shr:1 row_mask:0xf bank_mask:0xf
	v_mov_b32_dpp v120, v68 row_shr:1 row_mask:0xf bank_mask:0xf
	v_mov_b32_dpp v124, v100 row_shr:1 row_mask:0xf bank_mask:0xf
	v_mov_b32_dpp v121, v69 row_shr:1 row_mask:0xf bank_mask:0xf
	v_mov_b32_dpp v125, v101 row_shr:1 row_mask:0xf bank_mask:0xf
	v_pk_fma_f32 v[98:99], v[202:203], v[98:99], v[206:207]
	v_pk_fma_f32 v[100:101], v[204:205], v[100:101], v[208:209]
	v_pk_fma_f32 v[98:99], v[198:199], v[66:67], v[98:99]
	v_pk_fma_f32 v[100:101], v[200:201], v[68:69], v[100:101]
	v_pk_fma_f32 v[98:99], v[194:195], v[70:71], v[98:99]
	v_pk_fma_f32 v[100:101], v[196:197], v[72:73], v[100:101]
	v_pk_fma_f32 v[66:67], v[202:203], v[66:67], v[206:207]
	v_pk_fma_f32 v[68:69], v[204:205], v[68:69], v[208:209]
	v_pk_fma_f32 v[66:67], v[198:199], v[70:71], v[66:67]
	v_pk_fma_f32 v[68:69], v[200:201], v[72:73], v[68:69]
	v_pk_fma_f32 v[66:67], v[194:195], v[74:75], v[66:67]
	v_pk_fma_f32 v[68:69], v[196:197], v[76:77], v[68:69]
	v_pk_fma_f32 v[70:71], v[202:203], v[70:71], v[206:207]
	v_pk_fma_f32 v[72:73], v[204:205], v[72:73], v[208:209]
	v_pk_fma_f32 v[70:71], v[198:199], v[74:75], v[70:71]
	v_pk_fma_f32 v[72:73], v[200:201], v[76:77], v[72:73]
	v_pk_fma_f32 v[70:71], v[194:195], v[122:123], v[70:71]
	v_pk_fma_f32 v[72:73], v[196:197], v[124:125], v[72:73]
	v_pk_fma_f32 v[74:75], v[202:203], v[74:75], v[206:207]
	v_pk_fma_f32 v[76:77], v[204:205], v[76:77], v[208:209]
	v_pk_fma_f32 v[74:75], v[198:199], v[122:123], v[74:75]
	v_pk_fma_f32 v[76:77], v[200:201], v[124:125], v[76:77]
	v_pk_fma_f32 v[74:75], v[194:195], v[118:119], v[74:75]
	v_pk_fma_f32 v[76:77], v[196:197], v[120:121], v[76:77]
	s_cmp_lg_u32 s50, 0
	s_cbranch_scc1 .Lnepia_np2
	v_cmp_eq_u32_e32 vcc, 0, v224
	s_and_saveexec_b64 s[8:9], vcc
	s_add_u32 s48, s88, 0x2d00000
	s_addc_u32 s49, s89, 0
	global_store_dwordx4 v229, v[74:77], s[48:49] offset:16
	global_store_dwordx4 v231, v[70:73], s[48:49] offset:16
	s_or_b64 exec, exec, s[8:9]
	s_nop 1
.Lnepia_np2:
	s_waitcnt lgkmcnt(0)
	ds_read_b128 v[194:197], v226 offset:512
	ds_read_b128 v[198:201], v226 offset:1536
	ds_read_b128 v[202:205], v226 offset:2560
	ds_read_b128 v[206:209], v226 offset:3584
	ds_read_b128 v[118:121], v227 offset:4608
	ds_read_b128 v[122:125], v227 offset:5632
	v_mov_b32_dpp v162, v34 row_shr:1 row_mask:0xf bank_mask:0xf
	v_mov_b32_dpp v166, v82 row_shr:1 row_mask:0xf bank_mask:0xf
	v_mov_b32_dpp v163, v35 row_shr:1 row_mask:0xf bank_mask:0xf
	v_mov_b32_dpp v167, v83 row_shr:1 row_mask:0xf bank_mask:0xf
	v_mov_b32_dpp v164, v36 row_shr:1 row_mask:0xf bank_mask:0xf
	v_mov_b32_dpp v168, v84 row_shr:1 row_mask:0xf bank_mask:0xf
	v_mov_b32_dpp v165, v37 row_shr:1 row_mask:0xf bank_mask:0xf
	v_mov_b32_dpp v169, v85 row_shr:1 row_mask:0xf bank_mask:0xf
	v_pk_fma_f32 v[82:83], v[154:155], v[82:83], v[158:159]
	v_pk_fma_f32 v[84:85], v[156:157], v[84:85], v[160:161]
	v_pk_fma_f32 v[82:83], v[150:151], v[34:35], v[82:83]
	v_pk_fma_f32 v[84:85], v[152:153], v[36:37], v[84:85]
	v_pk_fma_f32 v[82:83], v[146:147], v[38:39], v[82:83]
	v_pk_fma_f32 v[84:85], v[148:149], v[40:41], v[84:85]
	v_pk_fma_f32 v[34:35], v[154:155], v[34:35], v[158:159]
	v_pk_fma_f32 v[36:37], v[156:157], v[36:37], v[160:161]
	v_pk_fma_f32 v[34:35], v[150:151], v[38:39], v[34:35]
	v_pk_fma_f32 v[36:37], v[152:153], v[40:41], v[36:37]
	v_pk_fma_f32 v[34:35], v[146:147], v[42:43], v[34:35]
	v_pk_fma_f32 v[36:37], v[148:149], v[44:45], v[36:37]
	v_pk_fma_f32 v[38:39], v[154:155], v[38:39], v[158:159]
	v_pk_fma_f32 v[40:41], v[156:157], v[40:41], v[160:161]
	v_pk_fma_f32 v[38:39], v[150:151], v[42:43], v[38:39]
	v_pk_fma_f32 v[40:41], v[152:153], v[44:45], v[40:41]
	v_pk_fma_f32 v[38:39], v[146:147], v[166:167], v[38:39]
	v_pk_fma_f32 v[40:41], v[148:149], v[168:169], v[40:41]
	v_pk_fma_f32 v[42:43], v[154:155], v[42:43], v[158:159]
	v_pk_fma_f32 v[44:45], v[156:157], v[44:45], v[160:161]
	v_pk_fma_f32 v[42:43], v[150:151], v[166:167], v[42:43]
	v_pk_fma_f32 v[44:45], v[152:153], v[168:169], v[44:45]
	v_pk_fma_f32 v[42:43], v[146:147], v[162:163], v[42:43]
	v_pk_fma_f32 v[44:45], v[148:149], v[164:165], v[44:45]
	s_cmp_lg_u32 s50, 0
	s_cbranch_scc1 .Lnepia_np3
	v_cmp_eq_u32_e32 vcc, 0, v224
	s_and_saveexec_b64 s[8:9], vcc
	s_add_u32 s48, s88, 0x2d00000
	s_addc_u32 s49, s89, 0
	global_store_dwordx4 v228, v[42:45], s[48:49] offset:16
	global_store_dwordx4 v230, v[38:41], s[48:49] offset:16
	s_or_b64 exec, exec, s[8:9]
	s_nop 1
.Lnepia_np3:
	v_pk_mul_f32 v[30:31], v[42:43], s[100:101]
	v_pk_mul_f32 v[32:33], v[44:45], s[100:101]
	v_pk_mul_f32 v[54:55], v[38:39], s[100:101]
	v_pk_mul_f32 v[56:57], v[40:41], s[100:101]
	v_exp_f32_e32 v30, v30
	v_exp_f32_e32 v31, v31
	v_exp_f32_e32 v32, v32
	v_exp_f32_e32 v33, v33
	v_exp_f32_e32 v54, v54
	v_exp_f32_e32 v55, v55
	v_exp_f32_e32 v56, v56
	v_exp_f32_e32 v57, v57
	v_pk_add_f32 v[30:31], v[30:31], s[98:99]
	v_pk_add_f32 v[32:33], v[32:33], s[98:99]
	v_pk_add_f32 v[54:55], v[54:55], s[98:99]
	v_pk_add_f32 v[56:57], v[56:57], s[98:99]
	v_rcp_f32_e32 v30, v30
	v_rcp_f32_e32 v31, v31
	v_rcp_f32_e32 v32, v32
	v_rcp_f32_e32 v33, v33
	v_rcp_f32_e32 v54, v54
	v_rcp_f32_e32 v55, v55
	v_rcp_f32_e32 v56, v56
	v_rcp_f32_e32 v57, v57
	v_pk_mul_f32 v[42:43], v[42:43], v[74:75]
	v_pk_mul_f32 v[44:45], v[44:45], v[76:77]
	v_pk_mul_f32 v[38:39], v[38:39], v[70:71]
	v_pk_mul_f32 v[40:41], v[40:41], v[72:73]
	v_pk_mul_f32 v[42:43], v[42:43], v[30:31]
	v_pk_mul_f32 v[44:45], v[44:45], v[32:33]
	v_pk_mul_f32 v[38:39], v[38:39], v[54:55]
	v_pk_mul_f32 v[40:41], v[40:41], v[56:57]
	v_pk_mul_f32 v[30:31], v[34:35], s[100:101]
	v_pk_mul_f32 v[32:33], v[36:37], s[100:101]
	v_pk_mul_f32 v[54:55], v[82:83], s[100:101]
	v_pk_mul_f32 v[56:57], v[84:85], s[100:101]
	v_exp_f32_e32 v30, v30
	v_exp_f32_e32 v31, v31
	v_exp_f32_e32 v32, v32
	v_exp_f32_e32 v33, v33
	v_exp_f32_e32 v54, v54
	v_exp_f32_e32 v55, v55
	v_exp_f32_e32 v56, v56
	v_exp_f32_e32 v57, v57
	v_pk_add_f32 v[30:31], v[30:31], s[98:99]
	v_pk_add_f32 v[32:33], v[32:33], s[98:99]
	v_pk_add_f32 v[54:55], v[54:55], s[98:99]
	v_pk_add_f32 v[56:57], v[56:57], s[98:99]
	v_rcp_f32_e32 v30, v30
	v_rcp_f32_e32 v31, v31
	v_rcp_f32_e32 v32, v32
	v_rcp_f32_e32 v33, v33
	v_rcp_f32_e32 v54, v54
	v_rcp_f32_e32 v55, v55
	v_rcp_f32_e32 v56, v56
	v_rcp_f32_e32 v57, v57
	v_pk_mul_f32 v[34:35], v[34:35], v[66:67]
	v_pk_mul_f32 v[36:37], v[36:37], v[68:69]
	v_pk_mul_f32 v[82:83], v[82:83], v[98:99]
	v_pk_mul_f32 v[84:85], v[84:85], v[100:101]
	v_pk_mul_f32 v[34:35], v[34:35], v[30:31]
	v_pk_mul_f32 v[36:37], v[36:37], v[32:33]
	v_pk_mul_f32 v[82:83], v[82:83], v[54:55]
	v_pk_mul_f32 v[84:85], v[84:85], v[56:57]
	s_add_u32 s48, s88, 0x9000000
	s_addc_u32 s49, s89, 0
	v_cvt_pk_bf16_f32 v134, v62, v63
	v_cvt_pk_bf16_f32 v135, v64, v65
	v_cvt_pk_bf16_f32 v136, v42, v43
	v_cvt_pk_bf16_f32 v137, v44, v45
	global_store_dwordx4 v244, v[134:137], s[48:49]
	v_add_u32_e32 v244, 0x1600, v244
	v_cvt_pk_bf16_f32 v74, v50, v51
	v_cvt_pk_bf16_f32 v75, v52, v53
	v_cvt_pk_bf16_f32 v76, v38, v39
	v_cvt_pk_bf16_f32 v77, v40, v41
	global_store_dwordx4 v244, v[74:77], s[48:49]
	v_add_u32_e32 v244, 0x1600, v244
	v_cvt_pk_bf16_f32 v134, v46, v47
	v_cvt_pk_bf16_f32 v135, v48, v49
	v_cvt_pk_bf16_f32 v136, v34, v35
	v_cvt_pk_bf16_f32 v137, v36, v37
	global_store_dwordx4 v244, v[134:137], s[48:49]
	v_add_u32_e32 v244, 0x1600, v244
	v_cvt_pk_bf16_f32 v74, v142, v143
	v_cvt_pk_bf16_f32 v75, v144, v145
	v_cvt_pk_bf16_f32 v76, v82, v83
	v_cvt_pk_bf16_f32 v77, v84, v85
	global_store_dwordx4 v244, v[74:77], s[48:49]
	v_add_u32_e32 v244, 0xffffbe00, v244
	s_waitcnt lgkmcnt(0)
	ds_read_b128 v[146:149], v226 offset:0
	ds_read_b128 v[150:153], v226 offset:1024
	ds_read_b128 v[154:157], v226 offset:2048
	ds_read_b128 v[158:161], v226 offset:3072
	ds_read_b128 v[162:165], v227 offset:4096
	ds_read_b128 v[166:169], v227 offset:5120
	v_mov_b32_dpp v118, v102 row_shr:1 row_mask:0xf bank_mask:0xf
	v_mov_b32_dpp v122, v126 row_shr:1 row_mask:0xf bank_mask:0xf
	v_mov_b32_dpp v119, v103 row_shr:1 row_mask:0xf bank_mask:0xf
	v_mov_b32_dpp v123, v127 row_shr:1 row_mask:0xf bank_mask:0xf
	v_mov_b32_dpp v120, v104 row_shr:1 row_mask:0xf bank_mask:0xf
	v_mov_b32_dpp v124, v128 row_shr:1 row_mask:0xf bank_mask:0xf
	v_mov_b32_dpp v121, v105 row_shr:1 row_mask:0xf bank_mask:0xf
	v_mov_b32_dpp v125, v129 row_shr:1 row_mask:0xf bank_mask:0xf
	v_pk_fma_f32 v[126:127], v[202:203], v[126:127], v[206:207]
	v_pk_fma_f32 v[128:129], v[204:205], v[128:129], v[208:209]
	v_pk_fma_f32 v[126:127], v[198:199], v[102:103], v[126:127]
	v_pk_fma_f32 v[128:129], v[200:201], v[104:105], v[128:129]
	v_pk_fma_f32 v[126:127], v[194:195], v[106:107], v[126:127]
	v_pk_fma_f32 v[128:129], v[196:197], v[108:109], v[128:129]
	v_pk_fma_f32 v[102:103], v[202:203], v[102:103], v[206:207]
	v_pk_fma_f32 v[104:105], v[204:205], v[104:105], v[208:209]
	v_pk_fma_f32 v[102:103], v[198:199], v[106:107], v[102:103]
	v_pk_fma_f32 v[104:105], v[200:201], v[108:109], v[104:105]
	v_pk_fma_f32 v[102:103], v[194:195], v[110:111], v[102:103]
	v_pk_fma_f32 v[104:105], v[196:197], v[112:113], v[104:105]
	v_pk_fma_f32 v[106:107], v[202:203], v[106:107], v[206:207]
	v_pk_fma_f32 v[108:109], v[204:205], v[108:109], v[208:209]
	v_pk_fma_f32 v[106:107], v[198:199], v[110:111], v[106:107]
	v_pk_fma_f32 v[108:109], v[200:201], v[112:113], v[108:109]
	v_pk_fma_f32 v[106:107], v[194:195], v[122:123], v[106:107]
	v_pk_fma_f32 v[108:109], v[196:197], v[124:125], v[108:109]
	v_pk_fma_f32 v[110:111], v[202:203], v[110:111], v[206:207]
	v_pk_fma_f32 v[112:113], v[204:205], v[112:113], v[208:209]
	v_pk_fma_f32 v[110:111], v[198:199], v[122:123], v[110:111]
	v_pk_fma_f32 v[112:113], v[200:201], v[124:125], v[112:113]
	v_pk_fma_f32 v[110:111], v[194:195], v[118:119], v[110:111]
	v_pk_fma_f32 v[112:113], v[196:197], v[120:121], v[112:113]
	s_waitcnt lgkmcnt(0)
	ds_read_b128 v[194:197], v226 offset:528
	ds_read_b128 v[198:201], v226 offset:1552
	ds_read_b128 v[202:205], v226 offset:2576
	ds_read_b128 v[206:209], v226 offset:3600
	ds_read_b128 v[118:121], v227 offset:4624
	ds_read_b128 v[122:125], v227 offset:5648
	v_mov_b32_dpp v162, v86 row_shr:1 row_mask:0xf bank_mask:0xf
	v_mov_b32_dpp v166, v114 row_shr:1 row_mask:0xf bank_mask:0xf
	v_mov_b32_dpp v163, v87 row_shr:1 row_mask:0xf bank_mask:0xf
	v_mov_b32_dpp v167, v115 row_shr:1 row_mask:0xf bank_mask:0xf
	v_mov_b32_dpp v164, v88 row_shr:1 row_mask:0xf bank_mask:0xf
	v_mov_b32_dpp v168, v116 row_shr:1 row_mask:0xf bank_mask:0xf
	v_mov_b32_dpp v165, v89 row_shr:1 row_mask:0xf bank_mask:0xf
	v_mov_b32_dpp v169, v117 row_shr:1 row_mask:0xf bank_mask:0xf
	v_pk_fma_f32 v[114:115], v[154:155], v[114:115], v[158:159]
	v_pk_fma_f32 v[116:117], v[156:157], v[116:117], v[160:161]
	v_pk_fma_f32 v[114:115], v[150:151], v[86:87], v[114:115]
	v_pk_fma_f32 v[116:117], v[152:153], v[88:89], v[116:117]
	v_pk_fma_f32 v[114:115], v[146:147], v[90:91], v[114:115]
	v_pk_fma_f32 v[116:117], v[148:149], v[92:93], v[116:117]
	v_pk_fma_f32 v[86:87], v[154:155], v[86:87], v[158:159]
	v_pk_fma_f32 v[88:89], v[156:157], v[88:89], v[160:161]
	v_pk_fma_f32 v[86:87], v[150:151], v[90:91], v[86:87]
	v_pk_fma_f32 v[88:89], v[152:153], v[92:93], v[88:89]
	v_pk_fma_f32 v[86:87], v[146:147], v[94:95], v[86:87]
	v_pk_fma_f32 v[88:89], v[148:149], v[96:97], v[88:89]
	v_pk_fma_f32 v[90:91], v[154:155], v[90:91], v[158:159]
	v_pk_fma_f32 v[92:93], v[156:157], v[92:93], v[160:161]
	v_pk_fma_f32 v[90:91], v[150:151], v[94:95], v[90:91]
	v_pk_fma_f32 v[92:93], v[152:153], v[96:97], v[92:93]
	v_pk_fma_f32 v[90:91], v[146:147], v[166:167], v[90:91]
	v_pk_fma_f32 v[92:93], v[148:149], v[168:169], v[92:93]
	v_pk_fma_f32 v[94:95], v[154:155], v[94:95], v[158:159]
	v_pk_fma_f32 v[96:97], v[156:157], v[96:97], v[160:161]
	v_pk_fma_f32 v[94:95], v[150:151], v[166:167], v[94:95]
	v_pk_fma_f32 v[96:97], v[152:153], v[168:169], v[96:97]
	v_pk_fma_f32 v[94:95], v[146:147], v[162:163], v[94:95]
	v_pk_fma_f32 v[96:97], v[148:149], v[164:165], v[96:97]
	v_pk_mul_f32 v[30:31], v[94:95], s[100:101]
	v_pk_mul_f32 v[32:33], v[96:97], s[100:101]
	v_pk_mul_f32 v[54:55], v[90:91], s[100:101]
	v_pk_mul_f32 v[56:57], v[92:93], s[100:101]
	v_exp_f32_e32 v30, v30
	v_exp_f32_e32 v31, v31
	v_exp_f32_e32 v32, v32
	v_exp_f32_e32 v33, v33
	v_exp_f32_e32 v54, v54
	v_exp_f32_e32 v55, v55
	v_exp_f32_e32 v56, v56
	v_exp_f32_e32 v57, v57
	v_pk_add_f32 v[30:31], v[30:31], s[98:99]
	v_pk_add_f32 v[32:33], v[32:33], s[98:99]
	v_pk_add_f32 v[54:55], v[54:55], s[98:99]
	v_pk_add_f32 v[56:57], v[56:57], s[98:99]
	v_rcp_f32_e32 v30, v30
	v_rcp_f32_e32 v31, v31
	v_rcp_f32_e32 v32, v32
	v_rcp_f32_e32 v33, v33
	v_rcp_f32_e32 v54, v54
	v_rcp_f32_e32 v55, v55
	v_rcp_f32_e32 v56, v56
	v_rcp_f32_e32 v57, v57
	v_pk_mul_f32 v[94:95], v[94:95], v[110:111]
	v_pk_mul_f32 v[96:97], v[96:97], v[112:113]
	v_pk_mul_f32 v[90:91], v[90:91], v[106:107]
	v_pk_mul_f32 v[92:93], v[92:93], v[108:109]
	v_pk_mul_f32 v[94:95], v[94:95], v[30:31]
	v_pk_mul_f32 v[96:97], v[96:97], v[32:33]
	v_pk_mul_f32 v[90:91], v[90:91], v[54:55]
	v_pk_mul_f32 v[92:93], v[92:93], v[56:57]
	v_pk_mul_f32 v[30:31], v[86:87], s[100:101]
	v_pk_mul_f32 v[32:33], v[88:89], s[100:101]
	v_pk_mul_f32 v[54:55], v[114:115], s[100:101]
	v_pk_mul_f32 v[56:57], v[116:117], s[100:101]
	v_exp_f32_e32 v30, v30
	v_exp_f32_e32 v31, v31
	v_exp_f32_e32 v32, v32
	v_exp_f32_e32 v33, v33
	v_exp_f32_e32 v54, v54
	v_exp_f32_e32 v55, v55
	v_exp_f32_e32 v56, v56
	v_exp_f32_e32 v57, v57
	v_pk_add_f32 v[30:31], v[30:31], s[98:99]
	v_pk_add_f32 v[32:33], v[32:33], s[98:99]
	v_pk_add_f32 v[54:55], v[54:55], s[98:99]
	v_pk_add_f32 v[56:57], v[56:57], s[98:99]
	v_rcp_f32_e32 v30, v30
	v_rcp_f32_e32 v31, v31
	v_rcp_f32_e32 v32, v32
	v_rcp_f32_e32 v33, v33
	v_rcp_f32_e32 v54, v54
	v_rcp_f32_e32 v55, v55
	v_rcp_f32_e32 v56, v56
	v_rcp_f32_e32 v57, v57
	v_pk_mul_f32 v[86:87], v[86:87], v[102:103]
	v_pk_mul_f32 v[88:89], v[88:89], v[104:105]
	v_pk_mul_f32 v[114:115], v[114:115], v[126:127]
	v_pk_mul_f32 v[116:117], v[116:117], v[128:129]
	v_pk_mul_f32 v[86:87], v[86:87], v[30:31]
	v_pk_mul_f32 v[88:89], v[88:89], v[32:33]
	v_pk_mul_f32 v[114:115], v[114:115], v[54:55]
	v_pk_mul_f32 v[116:117], v[116:117], v[56:57]
	s_waitcnt lgkmcnt(0)
	ds_read_b128 v[146:149], v226 offset:16
	ds_read_b128 v[150:153], v226 offset:1040
	ds_read_b128 v[154:157], v226 offset:2064
	ds_read_b128 v[158:161], v226 offset:3088
	ds_read_b128 v[162:165], v227 offset:4112
	ds_read_b128 v[166:169], v227 offset:5136
	v_mov_b32_dpp v118, v14 row_shr:1 row_mask:0xf bank_mask:0xf
	v_mov_b32_dpp v122, v58 row_shr:1 row_mask:0xf bank_mask:0xf
	v_mov_b32_dpp v119, v15 row_shr:1 row_mask:0xf bank_mask:0xf
	v_mov_b32_dpp v123, v59 row_shr:1 row_mask:0xf bank_mask:0xf
	v_mov_b32_dpp v120, v16 row_shr:1 row_mask:0xf bank_mask:0xf
	v_mov_b32_dpp v124, v60 row_shr:1 row_mask:0xf bank_mask:0xf
	v_mov_b32_dpp v121, v17 row_shr:1 row_mask:0xf bank_mask:0xf
	v_mov_b32_dpp v125, v61 row_shr:1 row_mask:0xf bank_mask:0xf
	v_pk_fma_f32 v[58:59], v[202:203], v[58:59], v[206:207]
	v_pk_fma_f32 v[60:61], v[204:205], v[60:61], v[208:209]
	v_pk_fma_f32 v[58:59], v[198:199], v[14:15], v[58:59]
	v_pk_fma_f32 v[60:61], v[200:201], v[16:17], v[60:61]
	v_pk_fma_f32 v[58:59], v[194:195], v[18:19], v[58:59]
	v_pk_fma_f32 v[60:61], v[196:197], v[20:21], v[60:61]
	v_pk_fma_f32 v[14:15], v[202:203], v[14:15], v[206:207]
	v_pk_fma_f32 v[16:17], v[204:205], v[16:17], v[208:209]
	v_pk_fma_f32 v[14:15], v[198:199], v[18:19], v[14:15]
	v_pk_fma_f32 v[16:17], v[200:201], v[20:21], v[16:17]
	v_pk_fma_f32 v[14:15], v[194:195], v[22:23], v[14:15]
	v_pk_fma_f32 v[16:17], v[196:197], v[24:25], v[16:17]
	v_pk_fma_f32 v[18:19], v[202:203], v[18:19], v[206:207]
	v_pk_fma_f32 v[20:21], v[204:205], v[20:21], v[208:209]
	v_pk_fma_f32 v[18:19], v[198:199], v[22:23], v[18:19]
	v_pk_fma_f32 v[20:21], v[200:201], v[24:25], v[20:21]
	v_pk_fma_f32 v[18:19], v[194:195], v[122:123], v[18:19]
	v_pk_fma_f32 v[20:21], v[196:197], v[124:125], v[20:21]
	v_pk_fma_f32 v[22:23], v[202:203], v[22:23], v[206:207]
	v_pk_fma_f32 v[24:25], v[204:205], v[24:25], v[208:209]
	v_pk_fma_f32 v[22:23], v[198:199], v[122:123], v[22:23]
	v_pk_fma_f32 v[24:25], v[200:201], v[124:125], v[24:25]
	v_pk_fma_f32 v[22:23], v[194:195], v[118:119], v[22:23]
	v_pk_fma_f32 v[24:25], v[196:197], v[120:121], v[24:25]
	s_waitcnt lgkmcnt(0)
	v_mov_b32_dpp v162, v2 row_shr:1 row_mask:0xf bank_mask:0xf
	v_mov_b32_dpp v166, v26 row_shr:1 row_mask:0xf bank_mask:0xf
	v_mov_b32_dpp v163, v3 row_shr:1 row_mask:0xf bank_mask:0xf
	v_mov_b32_dpp v167, v27 row_shr:1 row_mask:0xf bank_mask:0xf
	v_mov_b32_dpp v164, v4 row_shr:1 row_mask:0xf bank_mask:0xf
	v_mov_b32_dpp v168, v28 row_shr:1 row_mask:0xf bank_mask:0xf
	v_mov_b32_dpp v165, v5 row_shr:1 row_mask:0xf bank_mask:0xf
	v_mov_b32_dpp v169, v29 row_shr:1 row_mask:0xf bank_mask:0xf
	v_pk_fma_f32 v[26:27], v[154:155], v[26:27], v[158:159]
	v_pk_fma_f32 v[28:29], v[156:157], v[28:29], v[160:161]
	v_pk_fma_f32 v[26:27], v[150:151], v[2:3], v[26:27]
	v_pk_fma_f32 v[28:29], v[152:153], v[4:5], v[28:29]
	v_pk_fma_f32 v[26:27], v[146:147], v[6:7], v[26:27]
	v_pk_fma_f32 v[28:29], v[148:149], v[8:9], v[28:29]
	v_pk_fma_f32 v[2:3], v[154:155], v[2:3], v[158:159]
	v_pk_fma_f32 v[4:5], v[156:157], v[4:5], v[160:161]
	v_pk_fma_f32 v[2:3], v[150:151], v[6:7], v[2:3]
	v_pk_fma_f32 v[4:5], v[152:153], v[8:9], v[4:5]
	v_pk_fma_f32 v[2:3], v[146:147], v[10:11], v[2:3]
	v_pk_fma_f32 v[4:5], v[148:149], v[12:13], v[4:5]
	v_pk_fma_f32 v[6:7], v[154:155], v[6:7], v[158:159]
	v_pk_fma_f32 v[8:9], v[156:157], v[8:9], v[160:161]
	v_pk_fma_f32 v[6:7], v[150:151], v[10:11], v[6:7]
	v_pk_fma_f32 v[8:9], v[152:153], v[12:13], v[8:9]
	v_pk_fma_f32 v[6:7], v[146:147], v[166:167], v[6:7]
	v_pk_fma_f32 v[8:9], v[148:149], v[168:169], v[8:9]
	v_pk_fma_f32 v[10:11], v[154:155], v[10:11], v[158:159]
	v_pk_fma_f32 v[12:13], v[156:157], v[12:13], v[160:161]
	v_pk_fma_f32 v[10:11], v[150:151], v[166:167], v[10:11]
	v_pk_fma_f32 v[12:13], v[152:153], v[168:169], v[12:13]
	v_pk_fma_f32 v[10:11], v[146:147], v[162:163], v[10:11]
	v_pk_fma_f32 v[12:13], v[148:149], v[164:165], v[12:13]
	v_pk_mul_f32 v[30:31], v[10:11], s[100:101]
	v_pk_mul_f32 v[32:33], v[12:13], s[100:101]
	v_pk_mul_f32 v[54:55], v[6:7], s[100:101]
	v_pk_mul_f32 v[56:57], v[8:9], s[100:101]
	v_exp_f32_e32 v30, v30
	v_exp_f32_e32 v31, v31
	v_exp_f32_e32 v32, v32
	v_exp_f32_e32 v33, v33
	v_exp_f32_e32 v54, v54
	v_exp_f32_e32 v55, v55
	v_exp_f32_e32 v56, v56
	v_exp_f32_e32 v57, v57
	v_pk_add_f32 v[30:31], v[30:31], s[98:99]
	v_pk_add_f32 v[32:33], v[32:33], s[98:99]
	v_pk_add_f32 v[54:55], v[54:55], s[98:99]
	v_pk_add_f32 v[56:57], v[56:57], s[98:99]
	v_rcp_f32_e32 v30, v30
	v_rcp_f32_e32 v31, v31
	v_rcp_f32_e32 v32, v32
	v_rcp_f32_e32 v33, v33
	v_rcp_f32_e32 v54, v54
	v_rcp_f32_e32 v55, v55
	v_rcp_f32_e32 v56, v56
	v_rcp_f32_e32 v57, v57
	v_pk_mul_f32 v[10:11], v[10:11], v[22:23]
	v_pk_mul_f32 v[12:13], v[12:13], v[24:25]
	v_pk_mul_f32 v[6:7], v[6:7], v[18:19]
	v_pk_mul_f32 v[8:9], v[8:9], v[20:21]
	v_pk_mul_f32 v[10:11], v[10:11], v[30:31]
	v_pk_mul_f32 v[12:13], v[12:13], v[32:33]
	v_pk_mul_f32 v[6:7], v[6:7], v[54:55]
	v_pk_mul_f32 v[8:9], v[8:9], v[56:57]
	v_pk_mul_f32 v[30:31], v[2:3], s[100:101]
	v_pk_mul_f32 v[32:33], v[4:5], s[100:101]
	v_pk_mul_f32 v[54:55], v[26:27], s[100:101]
	v_pk_mul_f32 v[56:57], v[28:29], s[100:101]
	v_exp_f32_e32 v30, v30
	v_exp_f32_e32 v31, v31
	v_exp_f32_e32 v32, v32
	v_exp_f32_e32 v33, v33
	v_exp_f32_e32 v54, v54
	v_exp_f32_e32 v55, v55
	v_exp_f32_e32 v56, v56
	v_exp_f32_e32 v57, v57
	v_pk_add_f32 v[30:31], v[30:31], s[98:99]
	v_pk_add_f32 v[32:33], v[32:33], s[98:99]
	v_pk_add_f32 v[54:55], v[54:55], s[98:99]
	v_pk_add_f32 v[56:57], v[56:57], s[98:99]
	v_rcp_f32_e32 v30, v30
	v_rcp_f32_e32 v31, v31
	v_rcp_f32_e32 v32, v32
	v_rcp_f32_e32 v33, v33
	v_rcp_f32_e32 v54, v54
	v_rcp_f32_e32 v55, v55
	v_rcp_f32_e32 v56, v56
	v_rcp_f32_e32 v57, v57
	v_pk_mul_f32 v[2:3], v[2:3], v[14:15]
	v_pk_mul_f32 v[4:5], v[4:5], v[16:17]
	v_pk_mul_f32 v[26:27], v[26:27], v[58:59]
	v_pk_mul_f32 v[28:29], v[28:29], v[60:61]
	v_pk_mul_f32 v[2:3], v[2:3], v[30:31]
	v_pk_mul_f32 v[4:5], v[4:5], v[32:33]
	v_pk_mul_f32 v[26:27], v[26:27], v[54:55]
	v_pk_mul_f32 v[28:29], v[28:29], v[56:57]
	v_add_u32_e32 v244, 0xb0000, v244
	v_cvt_pk_bf16_f32 v110, v94, v95
	v_cvt_pk_bf16_f32 v111, v96, v97
	v_cvt_pk_bf16_f32 v112, v10, v11
	v_cvt_pk_bf16_f32 v113, v12, v13
	global_store_dwordx4 v244, v[110:113], s[48:49]
	v_add_u32_e32 v244, 0x1600, v244
	v_cvt_pk_bf16_f32 v22, v90, v91
	v_cvt_pk_bf16_f32 v23, v92, v93
	v_cvt_pk_bf16_f32 v24, v6, v7
	v_cvt_pk_bf16_f32 v25, v8, v9
	global_store_dwordx4 v244, v[22:25], s[48:49]
	v_add_u32_e32 v244, 0x1600, v244
	v_cvt_pk_bf16_f32 v110, v86, v87
	v_cvt_pk_bf16_f32 v111, v88, v89
	v_cvt_pk_bf16_f32 v112, v2, v3
	v_cvt_pk_bf16_f32 v113, v4, v5
	global_store_dwordx4 v244, v[110:113], s[48:49]
	v_add_u32_e32 v244, 0x1600, v244
	v_cvt_pk_bf16_f32 v22, v114, v115
	v_cvt_pk_bf16_f32 v23, v116, v117
	v_cvt_pk_bf16_f32 v24, v26, v27
	v_cvt_pk_bf16_f32 v25, v28, v29
	global_store_dwordx4 v244, v[22:25], s[48:49]
	s_cmp_lg_u32 s50, 1
	s_cselect_b64 s[8:9], -1, 0
	s_andn2_b64 vcc, exec, s[4:5]
	s_mov_b64 s[4:5], -1
	s_cbranch_vccnz .LBB0_553
	s_andn2_b64 vcc, exec, s[16:17]
	s_mov_b32 s3, s40
	s_mov_b64 s[28:29], s[94:95]
	s_mov_b64 s[4:5], s[36:37]
	s_cbranch_vccnz .LBB0_590
	s_ashr_i32 s3, s40, 5
	s_mul_hi_i32 s4, s3, 0x5800
	s_mulk_i32 s3, 0x5800
	v_readlane_b32 s5, v255, 14
	s_add_u32 s28, s5, s3
	v_readlane_b32 s3, v255, 15
	s_addc_u32 s29, s3, s4
	s_mov_b32 s3, s38
	s_mov_b64 s[4:5], s[62:63]

.LBB0_1309:
	s_add_u32 s7, s88, 0x1400000
	s_addc_u32 s56, s89, 0
	s_ashr_i32 s31, s30, 31
	s_waitcnt lgkmcnt(0)
	v_lshrrev_b32_e32 v3, 1, v170
	s_lshl_b64 s[8:9], s[30:31], 19
	v_and_b32_e32 v14, 24, v3
	v_lshrrev_b32_e32 v3, 5, v170
	s_add_u32 s8, s68, s8
	v_and_b32_e32 v3, 4, v3
	v_bfe_u32 v4, v170, 2, 2
	s_addc_u32 s9, s69, s9
	s_ashr_i32 s51, s50, 31
	v_lshlrev_b32_e32 v1, 4, v170
	v_and_b32_e32 v2, 32, v170
	v_bfe_u32 v12, v170, 2, 4
	v_or3_b32 v3, v3, v4, v14
	v_lshrrev_b32_e32 v4, 3, v170
	s_movk_i32 s23, 0x70
	s_lshl_b64 s[24:25], s[50:51], 19
	v_bitop3_b32 v10, v1, v2, 48 bitop3:0x6c
	v_and_b32_e32 v11, 64, v170
	v_and_or_b32 v5, v4, s23, v12
	s_movk_i32 s23, 0x60
	v_add_u32_e32 v13, 0x2000, v1
	s_add_u32 s52, s7, s24
	v_or_b32_e32 v2, v10, v11
	v_and_or_b32 v4, v4, s23, v3
	v_lshrrev_b32_e32 v1, 7, v13
	s_movk_i32 s23, 0xf0
	s_addc_u32 s53, s56, s25
	v_lshl_or_b32 v178, v4, 11, v2
	v_and_or_b32 v4, v1, s23, v12
	s_movk_i32 s23, 0xe0
	s_lshl_b32 s22, s22, 8
	s_lshr_b32 s34, s36, 6
	v_and_or_b32 v1, v1, s23, v3
	s_ashr_i32 s23, s22, 31
	s_lshr_b32 s37, s36, 8
	s_lshl_b32 s57, s34, 10
	s_and_b32 s26, s36, 0x3fffffc0
	s_and_b32 s27, s36, 0xc0
	s_lshl_b64 s[22:23], s[22:23], 2
	s_add_u32 s24, s4, s22
	v_lshl_or_b32 v182, v1, 11, v2
	v_or_b32_e32 v1, s27, v242
	s_addc_u32 s25, s5, s23
	s_bfe_u32 s4, s36, 0x10007
	v_lshlrev_b32_e32 v171, 2, v1
	s_mulk_i32 s4, 0xb00
	s_lshl_b32 s5, s50, 7
	v_mov_b32_e32 v1, 0x7f
	s_add_i32 s5, s5, s4
	v_bitop3_b32 v15, s27, v1, v242 bitop3:0xc8
	v_and_b32_e32 v6, 15, v5
	v_bfe_u32 v7, v5, 4, 2
	v_and_b32_e32 v5, 64, v5
	v_lshl_or_b32 v6, v6, 2, v7
	v_or_b32_e32 v5, v5, v6
	v_and_b32_e32 v6, 15, v4
	v_bfe_u32 v7, v4, 4, 2
	v_and_b32_e32 v4, 64, v4
	v_lshl_or_b32 v6, v6, 2, v7
	v_or_b32_e32 v4, v4, v6
	v_lshl_or_b32 v176, v5, 11, v2
	v_lshl_or_b32 v180, v4, 11, v2
	v_or_b32_e32 v2, s5, v15
	v_ashrrev_i32_e32 v3, 31, v2
	v_lshlrev_b64 v[2:3], 2, v[2:3]
	v_lshl_add_u64 v[4:5], s[0:1], 0, v[2:3]
	s_mul_i32 s1, s37, 0x5800
	s_mul_hi_u32 s0, s37, 0x5800
	s_add_u32 s1, s60, s1
	s_addc_u32 s0, s61, s0
	s_add_u32 s22, s1, 0x10800
	s_addc_u32 s23, s0, 0
	s_lshl_b32 s0, s26, 2
	s_add_i32 s0, s0, 0
	s_add_i32 s58, s0, 0x22100
	v_lshl_add_u64 v[2:3], s[22:23], 0, v[2:3]
	s_mov_b32 m0, s58
	s_add_i32 s59, s57, 0
	global_load_lds_dword v[2:3], off
	s_add_i32 m0, s0, 0x22900
	v_mov_b32_e32 v185, 0
	global_load_lds_dword v[4:5], off
	s_add_i32 m0, s0, 0x23100
	v_mov_b32_e32 v179, v185
	global_load_lds_dword v171, s[24:25]
	s_add_i32 m0, s59, 0x10000
	v_mov_b32_e32 v183, v185
	global_load_lds_dwordx4 v178, s[52:53]
	s_add_i32 m0, s59, 0x12000
	s_add_u32 s0, s52, 0x40000
	global_load_lds_dwordx4 v182, s[52:53]
	s_addc_u32 s1, s53, 0
	s_add_i32 m0, s59, 0x14000
	s_add_i32 s62, s59, 0x2000
	global_load_lds_dwordx4 v178, s[0:1]
	s_add_i32 m0, s59, 0x16000
	v_mov_b32_e32 v177, v185
	global_load_lds_dwordx4 v182, s[0:1]
	s_mov_b32 m0, s59
	s_add_u32 s0, s8, 0x40000
	global_load_lds_dwordx4 v176, s[8:9]
	s_mov_b32 m0, s62
	s_addc_u32 s1, s9, 0
	s_add_i32 s63, s59, 0x4000
	global_load_lds_dwordx4 v180, s[8:9]
	s_mov_b32 m0, s63
	s_add_i32 s64, s59, 0x6000
	global_load_lds_dwordx4 v176, s[0:1]
	s_mov_b32 m0, s64
	v_mov_b32_e32 v181, v185
	global_load_lds_dwordx4 v180, s[0:1]
	s_cmp_eq_u32 s37, 1
	s_movk_i32 s65, 0x5800
	s_mov_b32 s31, 0
	v_lshl_add_u64 v[8:9], s[52:53], 0, v[178:179]
	v_lshl_add_u64 v[6:7], s[52:53], 0, v[182:183]
	v_lshl_add_u64 v[2:3], s[8:9], 0, v[176:177]
	s_cselect_b64 s[24:25], -1, 0
	s_cmp_lg_u32 s37, 1
	v_lshl_add_u64 v[4:5], s[8:9], 0, v[180:181]
	s_cbranch_scc1 .LBB0_1311
	s_barrier
.LBB0_1311:
	s_add_u32 s26, s88, 0x2a00000
	s_addc_u32 s27, s89, 0
	s_add_u32 s28, s88, 0x2d00000
	s_addc_u32 s29, s89, 0
	s_lshl_b32 s0, s34, 5
	s_mov_b64 s[34:35], 0x80
	s_and_b32 s38, s0, 0x60
	s_add_i32 m0, s59, 0x18000
	v_lshl_add_u64 v[8:9], v[8:9], 0, s[34:35]
	s_lshl_b32 s5, s37, 13
	s_lshl_b32 s39, s38, 7
	s_waitcnt vmcnt(2)
	s_barrier
	global_load_lds_dwordx4 v[8:9], off
	v_lshl_add_u64 v[6:7], v[6:7], 0, s[34:35]
	s_add_i32 m0, s59, 0x1a000
	s_add_i32 s70, s59, 0x8000
	s_add_i32 s71, s59, 0xa000
	global_load_lds_dwordx4 v[6:7], off
	v_lshl_add_u64 v[2:3], v[2:3], 0, s[34:35]
	s_mov_b32 m0, s70
	s_add_u32 s0, s52, 0x40080
	global_load_lds_dwordx4 v[2:3], off
	v_lshl_add_u64 v[2:3], v[4:5], 0, s[34:35]
	s_mov_b32 m0, s71
	s_addc_u32 s1, s53, 0
	global_load_lds_dwordx4 v[2:3], off
	s_add_i32 m0, s59, 0x1c000
	v_lshl_add_u64 v[2:3], s[0:1], 0, v[178:179]
	global_load_lds_dwordx4 v[2:3], off
	v_lshl_add_u64 v[2:3], s[0:1], 0, v[182:183]
	s_add_i32 m0, s59, 0x1e000
	v_and_b32_e32 v1, 15, v170
	global_load_lds_dwordx4 v[2:3], off
	v_lshlrev_b32_e32 v2, 1, v14
	v_lshlrev_b32_e32 v5, 6, v170
	s_movk_i32 s0, 0x3c0
	v_lshl_or_b32 v3, v1, 6, v2
	v_and_b32_e32 v4, 32, v172
	v_and_or_b32 v2, v5, s0, v2
	v_bitop3_b32 v175, s39, v2, v4 bitop3:0xf6
	s_lshl_b32 s40, s37, 9
	v_lshlrev_b32_e32 v2, 8, v1
	v_bitop3_b32 v3, v3, s5, v4 bitop3:0xde
	v_or_b32_e32 v186, s38, v14
	s_and_b32 s72, s36, 0xffffff00
	v_add_u32_e32 v4, s40, v2
	v_or_b32_e32 v4, v4, v186
	s_cmpk_gt_u32 s36, 0xff
	v_or_b32_e32 v187, s4, v15
	v_cmp_lt_u32_e64 s[0:1], 13, v1
	v_lshlrev_b32_e32 v4, 2, v4
	v_or_b32_e32 v2, v186, v2
	s_cselect_b64 s[4:5], -1, 0
	v_lshl_or_b32 v173, s37, 6, v1
	v_add_u32_e32 v212, 0xffffc800, v4
	v_add_u32_e32 v213, 0xffffd800, v4
	v_or_b32_e32 v4, 0xfffff000, v2
	s_and_b64 s[36:37], s[0:1], s[4:5]
	s_add_i32 s4, s40, 0x400
	v_or_b32_e32 v2, 0xfffff004, v2
	v_add_lshl_u32 v217, v2, s40, 2
	v_add_lshl_u32 v218, v2, s4, 2
	v_lshlrev_b32_e32 v2, 8, v170
	v_add_lshl_u32 v215, v4, s40, 2
	v_add_lshl_u32 v216, v4, s4, 2
	v_and_b32_e32 v2, 0x38000, v2
	v_lshlrev_b32_e32 v4, 11, v12
	v_cmp_gt_u32_e32 vcc, 2, v1
	v_or3_b32 v2, v10, v2, v4
	s_and_b64 s[38:39], s[18:19], vcc
	s_ashr_i32 s73, s33, 31
	s_ashr_i32 s74, s2, 31
	v_mov_b32_e32 v188, v176
	v_lshlrev_b32_e32 v2, 4, v13
	s_waitcnt vmcnt(6)
	s_add_u32 s40, s60, 0x1b800
	v_and_b32_e32 v2, 0x78000, v2
	s_addc_u32 s41, s61, 0
	v_or3_b32 v2, v10, v2, v4
	s_add_i32 s75, 0, 0x10000
	s_add_i32 s76, 0, 0x14000
	v_add_u32_e32 v214, -14, v1
	v_mov_b32_e32 v189, v185
	v_mov_b32_e32 v190, v180
	v_mov_b32_e32 v191, v185
	v_mov_b64_e32 v[192:193], 0x580
	v_mov_b64_e32 v[194:195], 0x57f
	v_add_u32_e32 v219, s75, v175
	v_add_u32_e32 v220, s76, v175
	v_add_u32_e32 v221, 0, v3
	v_mov_b32_e32 v222, 0x358637bd
	s_add_i32 s77, 0, 0x20000
	s_add_i32 s78, 0, 0x20010
	s_add_i32 s79, 0, 0x20200
	s_add_i32 s80, 0, 0x20210
	s_movk_i32 s81, 0x1600
	v_lshlrev_b32_e32 v184, 1, v186
	s_barrier
	s_branch .LBB0_1314

.LBB0_1320:
	s_mov_b32 s98, 1.0
	s_mov_b32 s99, 1.0
	s_mov_b32 s100, 0xbfb8aa3b
	s_mov_b32 s101, 0xbfb8aa3b
	v_readfirstlane_b32 s54, v170
	v_and_b32_e32 v224, 15, v170
	v_bfe_u32 v245, v170, 4, 2
	s_lshr_b32 s54, s54, 6
	s_and_b32 s55, s54, 3
	s_lshr_b32 s54, s54, 2
	s_lshl_b32 s55, s55, 7
	v_lshl_add_u32 v225, v245, 5, s55
	s_bitcmp1_b32 s31, 0
	s_cselect_b32 s51, 0x1800, 0
	s_add_i32 s51, s51, 0x22100
	v_add_u32_e32 v226, s51, v225
	s_lshl_b32 s55, s54, 8
	s_add_i32 s55, s55, s51
	v_lshl_add_u32 v245, v224, 4, s55
	ds_read_b128 v[146:149], v245 offset:4096
	ds_read_b128 v[150:153], v245 offset:4608
	ds_read_b128 v[154:157], v226 offset:5120
	ds_read_b128 v[158:161], v226 offset:5136
	ds_read_b128 v[162:165], v226 offset:5632
	ds_read_b128 v[166:169], v226 offset:5648
	s_lshl_b32 s55, s54, 11
	s_add_i32 s55, s55, 0x1f800
	v_add_u32_e32 v227, s55, v225
	s_mul_i32 s55, s30, 0xb000
	s_lshl_b32 s51, s50, 9
	s_add_i32 s55, s55, s51
	v_add_u32_e32 v228, s55, v225
	v_add_u32_e32 v229, 0x2c00, v228
	v_add_u32_e32 v230, 0x5800, v228
	v_add_u32_e32 v231, 0x8400, v228
	s_lshl_b32 s55, s30, 8
	s_lshl_b32 s51, s54, 6
	s_add_i32 s55, s55, s51
	v_lshl_add_u32 v244, v224, 2, s55
	v_mul_u32_u24_e32 v244, 0x1600, v244
	s_lshl_b32 s51, s50, 8
	v_lshrrev_b32_e32 v245, 1, v225
	v_add3_u32 v244, v244, v245, s51
	v_mov_b32_e32 v245, 0x358637bd
	s_waitcnt lgkmcnt(4)
	v_fmamk_f32 v146, v146, 0x3a800000, v245
	v_fmamk_f32 v147, v147, 0x3a800000, v245
	v_fmamk_f32 v148, v148, 0x3a800000, v245
	v_fmamk_f32 v149, v149, 0x3a800000, v245
	v_fmamk_f32 v150, v150, 0x3a800000, v245
	v_fmamk_f32 v151, v151, 0x3a800000, v245
	v_fmamk_f32 v152, v152, 0x3a800000, v245
	v_fmamk_f32 v153, v153, 0x3a800000, v245
	v_rsq_f32_e32 v146, v146
	v_rsq_f32_e32 v147, v147
	v_rsq_f32_e32 v148, v148
	v_rsq_f32_e32 v149, v149
	v_rsq_f32_e32 v150, v150
	v_rsq_f32_e32 v151, v151
	v_rsq_f32_e32 v152, v152
	v_rsq_f32_e32 v153, v153
	s_waitcnt lgkmcnt(0)
	v_pk_fma_f32 v[62:63], v[62:63], v[146:147], v[154:155] op_sel:[0,0,0] op_sel_hi:[1,0,1]
	v_pk_fma_f32 v[64:65], v[64:65], v[146:147], v[156:157] op_sel:[0,0,0] op_sel_hi:[1,0,1]
	v_pk_fma_f32 v[42:43], v[42:43], v[146:147], v[158:159] op_sel:[0,0,0] op_sel_hi:[1,0,1]
	v_pk_fma_f32 v[44:45], v[44:45], v[146:147], v[160:161] op_sel:[0,0,0] op_sel_hi:[1,0,1]
	v_pk_fma_f32 v[134:135], v[134:135], v[146:147], v[162:163] op_sel:[0,0,0] op_sel_hi:[1,0,1]
	v_pk_fma_f32 v[136:137], v[136:137], v[146:147], v[164:165] op_sel:[0,0,0] op_sel_hi:[1,0,1]
	v_pk_fma_f32 v[74:75], v[74:75], v[146:147], v[166:167] op_sel:[0,0,0] op_sel_hi:[1,0,1]
	v_pk_fma_f32 v[76:77], v[76:77], v[146:147], v[168:169] op_sel:[0,0,0] op_sel_hi:[1,0,1]
	v_pk_fma_f32 v[50:51], v[50:51], v[146:147], v[154:155] op_sel:[0,1,0] op_sel_hi:[1,1,1]
	v_pk_fma_f32 v[52:53], v[52:53], v[146:147], v[156:157] op_sel:[0,1,0] op_sel_hi:[1,1,1]
	v_pk_fma_f32 v[38:39], v[38:39], v[146:147], v[158:159] op_sel:[0,1,0] op_sel_hi:[1,1,1]
	v_pk_fma_f32 v[40:41], v[40:41], v[146:147], v[160:161] op_sel:[0,1,0] op_sel_hi:[1,1,1]
	v_pk_fma_f32 v[130:131], v[130:131], v[146:147], v[162:163] op_sel:[0,1,0] op_sel_hi:[1,1,1]
	v_pk_fma_f32 v[132:133], v[132:133], v[146:147], v[164:165] op_sel:[0,1,0] op_sel_hi:[1,1,1]
	v_pk_fma_f32 v[70:71], v[70:71], v[146:147], v[166:167] op_sel:[0,1,0] op_sel_hi:[1,1,1]
	v_pk_fma_f32 v[72:73], v[72:73], v[146:147], v[168:169] op_sel:[0,1,0] op_sel_hi:[1,1,1]
	v_pk_fma_f32 v[46:47], v[46:47], v[148:149], v[154:155] op_sel:[0,0,0] op_sel_hi:[1,0,1]
	v_pk_fma_f32 v[48:49], v[48:49], v[148:149], v[156:157] op_sel:[0,0,0] op_sel_hi:[1,0,1]
	v_pk_fma_f32 v[34:35], v[34:35], v[148:149], v[158:159] op_sel:[0,0,0] op_sel_hi:[1,0,1]
	v_pk_fma_f32 v[36:37], v[36:37], v[148:149], v[160:161] op_sel:[0,0,0] op_sel_hi:[1,0,1]
	v_pk_fma_f32 v[78:79], v[78:79], v[148:149], v[162:163] op_sel:[0,0,0] op_sel_hi:[1,0,1]
	v_pk_fma_f32 v[80:81], v[80:81], v[148:149], v[164:165] op_sel:[0,0,0] op_sel_hi:[1,0,1]
	v_pk_fma_f32 v[66:67], v[66:67], v[148:149], v[166:167] op_sel:[0,0,0] op_sel_hi:[1,0,1]
	v_pk_fma_f32 v[68:69], v[68:69], v[148:149], v[168:169] op_sel:[0,0,0] op_sel_hi:[1,0,1]
	v_pk_fma_f32 v[142:143], v[142:143], v[148:149], v[154:155] op_sel:[0,1,0] op_sel_hi:[1,1,1]
	v_pk_fma_f32 v[144:145], v[144:145], v[148:149], v[156:157] op_sel:[0,1,0] op_sel_hi:[1,1,1]
	v_pk_fma_f32 v[82:83], v[82:83], v[148:149], v[158:159] op_sel:[0,1,0] op_sel_hi:[1,1,1]
	v_pk_fma_f32 v[84:85], v[84:85], v[148:149], v[160:161] op_sel:[0,1,0] op_sel_hi:[1,1,1]
	v_pk_fma_f32 v[138:139], v[138:139], v[148:149], v[162:163] op_sel:[0,1,0] op_sel_hi:[1,1,1]
	v_pk_fma_f32 v[140:141], v[140:141], v[148:149], v[164:165] op_sel:[0,1,0] op_sel_hi:[1,1,1]
	v_pk_fma_f32 v[98:99], v[98:99], v[148:149], v[166:167] op_sel:[0,1,0] op_sel_hi:[1,1,1]
	v_pk_fma_f32 v[100:101], v[100:101], v[148:149], v[168:169] op_sel:[0,1,0] op_sel_hi:[1,1,1]
	v_pk_fma_f32 v[94:95], v[94:95], v[150:151], v[154:155] op_sel:[0,0,0] op_sel_hi:[1,0,1]
	v_pk_fma_f32 v[96:97], v[96:97], v[150:151], v[156:157] op_sel:[0,0,0] op_sel_hi:[1,0,1]
	v_pk_fma_f32 v[10:11], v[10:11], v[150:151], v[158:159] op_sel:[0,0,0] op_sel_hi:[1,0,1]
	v_pk_fma_f32 v[12:13], v[12:13], v[150:151], v[160:161] op_sel:[0,0,0] op_sel_hi:[1,0,1]
	v_pk_fma_f32 v[110:111], v[110:111], v[150:151], v[162:163] op_sel:[0,0,0] op_sel_hi:[1,0,1]
	v_pk_fma_f32 v[112:113], v[112:113], v[150:151], v[164:165] op_sel:[0,0,0] op_sel_hi:[1,0,1]
	v_pk_fma_f32 v[22:23], v[22:23], v[150:151], v[166:167] op_sel:[0,0,0] op_sel_hi:[1,0,1]
	v_pk_fma_f32 v[24:25], v[24:25], v[150:151], v[168:169] op_sel:[0,0,0] op_sel_hi:[1,0,1]
	v_pk_fma_f32 v[90:91], v[90:91], v[150:151], v[154:155] op_sel:[0,1,0] op_sel_hi:[1,1,1]
	v_pk_fma_f32 v[92:93], v[92:93], v[150:151], v[156:157] op_sel:[0,1,0] op_sel_hi:[1,1,1]
	v_pk_fma_f32 v[6:7], v[6:7], v[150:151], v[158:159] op_sel:[0,1,0] op_sel_hi:[1,1,1]
	v_pk_fma_f32 v[8:9], v[8:9], v[150:151], v[160:161] op_sel:[0,1,0] op_sel_hi:[1,1,1]
	v_pk_fma_f32 v[106:107], v[106:107], v[150:151], v[162:163] op_sel:[0,1,0] op_sel_hi:[1,1,1]
	v_pk_fma_f32 v[108:109], v[108:109], v[150:151], v[164:165] op_sel:[0,1,0] op_sel_hi:[1,1,1]
	v_pk_fma_f32 v[18:19], v[18:19], v[150:151], v[166:167] op_sel:[0,1,0] op_sel_hi:[1,1,1]
	v_pk_fma_f32 v[20:21], v[20:21], v[150:151], v[168:169] op_sel:[0,1,0] op_sel_hi:[1,1,1]
	v_pk_fma_f32 v[86:87], v[86:87], v[152:153], v[154:155] op_sel:[0,0,0] op_sel_hi:[1,0,1]
	v_pk_fma_f32 v[88:89], v[88:89], v[152:153], v[156:157] op_sel:[0,0,0] op_sel_hi:[1,0,1]
	v_pk_fma_f32 v[2:3], v[2:3], v[152:153], v[158:159] op_sel:[0,0,0] op_sel_hi:[1,0,1]
	v_pk_fma_f32 v[4:5], v[4:5], v[152:153], v[160:161] op_sel:[0,0,0] op_sel_hi:[1,0,1]
	v_pk_fma_f32 v[102:103], v[102:103], v[152:153], v[162:163] op_sel:[0,0,0] op_sel_hi:[1,0,1]
	v_pk_fma_f32 v[104:105], v[104:105], v[152:153], v[164:165] op_sel:[0,0,0] op_sel_hi:[1,0,1]
	v_pk_fma_f32 v[14:15], v[14:15], v[152:153], v[166:167] op_sel:[0,0,0] op_sel_hi:[1,0,1]
	v_pk_fma_f32 v[16:17], v[16:17], v[152:153], v[168:169] op_sel:[0,0,0] op_sel_hi:[1,0,1]
	v_pk_fma_f32 v[114:115], v[114:115], v[152:153], v[154:155] op_sel:[0,1,0] op_sel_hi:[1,1,1]
	v_pk_fma_f32 v[116:117], v[116:117], v[152:153], v[156:157] op_sel:[0,1,0] op_sel_hi:[1,1,1]
	v_pk_fma_f32 v[26:27], v[26:27], v[152:153], v[158:159] op_sel:[0,1,0] op_sel_hi:[1,1,1]
	v_pk_fma_f32 v[28:29], v[28:29], v[152:153], v[160:161] op_sel:[0,1,0] op_sel_hi:[1,1,1]
	v_pk_fma_f32 v[126:127], v[126:127], v[152:153], v[162:163] op_sel:[0,1,0] op_sel_hi:[1,1,1]
	v_pk_fma_f32 v[128:129], v[128:129], v[152:153], v[164:165] op_sel:[0,1,0] op_sel_hi:[1,1,1]
	v_pk_fma_f32 v[58:59], v[58:59], v[152:153], v[166:167] op_sel:[0,1,0] op_sel_hi:[1,1,1]
	v_pk_fma_f32 v[60:61], v[60:61], v[152:153], v[168:169] op_sel:[0,1,0] op_sel_hi:[1,1,1]
	v_cmp_eq_u32_e32 vcc, 15, v224
	s_and_saveexec_b64 s[8:9], vcc
	ds_write_b128 v227, v[46:49] offset:2048
	ds_write_b128 v227, v[34:37] offset:2064
	ds_write_b128 v227, v[78:81] offset:2560
	ds_write_b128 v227, v[66:69] offset:2576
	ds_write_b128 v227, v[142:145] offset:3072
	ds_write_b128 v227, v[82:85] offset:3088
	ds_write_b128 v227, v[138:141] offset:3584
	ds_write_b128 v227, v[98:101] offset:3600
	ds_write_b128 v227, v[86:89] offset:6144
	ds_write_b128 v227, v[2:5] offset:6160
	ds_write_b128 v227, v[102:105] offset:6656
	ds_write_b128 v227, v[14:17] offset:6672
	ds_write_b128 v227, v[114:117] offset:7168
	ds_write_b128 v227, v[26:29] offset:7184
	ds_write_b128 v227, v[126:129] offset:7680
	ds_write_b128 v227, v[58:61] offset:7696
	s_cmp_lg_u32 s54, 1
	s_cbranch_scc1 .Lnepib_nohalo
	s_add_u32 s52, s88, 0x2a00000
	s_addc_u32 s53, s89, 0
	global_store_dwordx4 v228, v[86:89], s[52:53] offset:0
	global_store_dwordx4 v228, v[2:5], s[52:53] offset:16
	global_store_dwordx4 v229, v[102:105], s[52:53] offset:0
	global_store_dwordx4 v229, v[14:17], s[52:53] offset:16
	global_store_dwordx4 v230, v[114:117], s[52:53] offset:0
	global_store_dwordx4 v230, v[26:29], s[52:53] offset:16
	global_store_dwordx4 v231, v[126:129], s[52:53] offset:0
	global_store_dwordx4 v231, v[58:61], s[52:53] offset:16
.Lnepib_nohalo:
	s_or_b64 exec, exec, s[8:9]
	s_waitcnt lgkmcnt(0)
	s_barrier
	ds_read_b128 v[196:199], v226 offset:512
	ds_read_b128 v[200:203], v226 offset:1536
	ds_read_b128 v[204:207], v226 offset:2560
	ds_read_b128 v[208:211], v226 offset:3584
	s_cmp_eq_u32 s54, 0
	s_cbranch_scc1 .Lnepib_z0
	ds_read_b128 v[118:121], v227 offset:512
	ds_read_b128 v[122:125], v227 offset:1536
	s_branch .Lnepib_j0

.Lnepib_j0:
	s_waitcnt lgkmcnt(0)
	ds_read_b128 v[146:149], v226 offset:0
	ds_read_b128 v[150:153], v226 offset:1024
	ds_read_b128 v[154:157], v226 offset:2048
	ds_read_b128 v[158:161], v226 offset:3072
	s_cmp_eq_u32 s54, 0
	s_cbranch_scc1 .Lnepib_z1
	ds_read_b128 v[162:165], v227 offset:0
	ds_read_b128 v[166:169], v227 offset:1024
	s_branch .Lnepib_j1

.Lnepib_j1:
	v_mov_b32_dpp v118, v78 row_shr:1 row_mask:0xf bank_mask:0xf
	v_mov_b32_dpp v122, v138 row_shr:1 row_mask:0xf bank_mask:0xf
	v_mov_b32_dpp v119, v79 row_shr:1 row_mask:0xf bank_mask:0xf
	v_mov_b32_dpp v123, v139 row_shr:1 row_mask:0xf bank_mask:0xf
	v_mov_b32_dpp v120, v80 row_shr:1 row_mask:0xf bank_mask:0xf
	v_mov_b32_dpp v124, v140 row_shr:1 row_mask:0xf bank_mask:0xf
	v_mov_b32_dpp v121, v81 row_shr:1 row_mask:0xf bank_mask:0xf
	v_mov_b32_dpp v125, v141 row_shr:1 row_mask:0xf bank_mask:0xf
	v_pk_fma_f32 v[138:139], v[204:205], v[138:139], v[208:209]
	v_pk_fma_f32 v[140:141], v[206:207], v[140:141], v[210:211]
	v_pk_fma_f32 v[138:139], v[200:201], v[78:79], v[138:139]
	v_pk_fma_f32 v[140:141], v[202:203], v[80:81], v[140:141]
	v_pk_fma_f32 v[138:139], v[196:197], v[130:131], v[138:139]
	v_pk_fma_f32 v[140:141], v[198:199], v[132:133], v[140:141]
	v_pk_fma_f32 v[78:79], v[204:205], v[78:79], v[208:209]
	v_pk_fma_f32 v[80:81], v[206:207], v[80:81], v[210:211]
	v_pk_fma_f32 v[78:79], v[200:201], v[130:131], v[78:79]
	v_pk_fma_f32 v[80:81], v[202:203], v[132:133], v[80:81]
	v_pk_fma_f32 v[78:79], v[196:197], v[134:135], v[78:79]
	v_pk_fma_f32 v[80:81], v[198:199], v[136:137], v[80:81]
	v_pk_fma_f32 v[130:131], v[204:205], v[130:131], v[208:209]
	v_pk_fma_f32 v[132:133], v[206:207], v[132:133], v[210:211]
	v_pk_fma_f32 v[130:131], v[200:201], v[134:135], v[130:131]
	v_pk_fma_f32 v[132:133], v[202:203], v[136:137], v[132:133]
	v_pk_fma_f32 v[130:131], v[196:197], v[122:123], v[130:131]
	v_pk_fma_f32 v[132:133], v[198:199], v[124:125], v[132:133]
	v_pk_fma_f32 v[134:135], v[204:205], v[134:135], v[208:209]
	v_pk_fma_f32 v[136:137], v[206:207], v[136:137], v[210:211]
	v_pk_fma_f32 v[134:135], v[200:201], v[122:123], v[134:135]
	v_pk_fma_f32 v[136:137], v[202:203], v[124:125], v[136:137]
	v_pk_fma_f32 v[134:135], v[196:197], v[118:119], v[134:135]
	v_pk_fma_f32 v[136:137], v[198:199], v[120:121], v[136:137]
	s_cmp_lg_u32 s54, 0
	s_cbranch_scc1 .Lnepib_np0
	v_cmp_eq_u32_e32 vcc, 0, v224
	s_and_saveexec_b64 s[8:9], vcc
	s_add_u32 s52, s88, 0x2d00000
	s_addc_u32 s53, s89, 0
	global_store_dwordx4 v229, v[134:137], s[52:53] offset:0
	global_store_dwordx4 v231, v[130:133], s[52:53] offset:0
	s_or_b64 exec, exec, s[8:9]
	s_nop 1
.Lnepib_np0:
	s_waitcnt lgkmcnt(0)
	ds_read_b128 v[196:199], v226 offset:528
	ds_read_b128 v[200:203], v226 offset:1552
	ds_read_b128 v[204:207], v226 offset:2576
	ds_read_b128 v[208:211], v226 offset:3600
	s_cmp_eq_u32 s54, 0
	s_cbranch_scc1 .Lnepib_z2
	ds_read_b128 v[118:121], v227 offset:528
	ds_read_b128 v[122:125], v227 offset:1552
	s_branch .Lnepib_j2

.Lnepib_j2:
	v_mov_b32_dpp v162, v46 row_shr:1 row_mask:0xf bank_mask:0xf
	v_mov_b32_dpp v166, v142 row_shr:1 row_mask:0xf bank_mask:0xf
	v_mov_b32_dpp v163, v47 row_shr:1 row_mask:0xf bank_mask:0xf
	v_mov_b32_dpp v167, v143 row_shr:1 row_mask:0xf bank_mask:0xf
	v_mov_b32_dpp v164, v48 row_shr:1 row_mask:0xf bank_mask:0xf
	v_mov_b32_dpp v168, v144 row_shr:1 row_mask:0xf bank_mask:0xf
	v_mov_b32_dpp v165, v49 row_shr:1 row_mask:0xf bank_mask:0xf
	v_mov_b32_dpp v169, v145 row_shr:1 row_mask:0xf bank_mask:0xf
	v_pk_fma_f32 v[142:143], v[154:155], v[142:143], v[158:159]
	v_pk_fma_f32 v[144:145], v[156:157], v[144:145], v[160:161]
	v_pk_fma_f32 v[142:143], v[150:151], v[46:47], v[142:143]
	v_pk_fma_f32 v[144:145], v[152:153], v[48:49], v[144:145]
	v_pk_fma_f32 v[142:143], v[146:147], v[50:51], v[142:143]
	v_pk_fma_f32 v[144:145], v[148:149], v[52:53], v[144:145]
	v_pk_fma_f32 v[46:47], v[154:155], v[46:47], v[158:159]
	v_pk_fma_f32 v[48:49], v[156:157], v[48:49], v[160:161]
	v_pk_fma_f32 v[46:47], v[150:151], v[50:51], v[46:47]
	v_pk_fma_f32 v[48:49], v[152:153], v[52:53], v[48:49]
	v_pk_fma_f32 v[46:47], v[146:147], v[62:63], v[46:47]
	v_pk_fma_f32 v[48:49], v[148:149], v[64:65], v[48:49]
	v_pk_fma_f32 v[50:51], v[154:155], v[50:51], v[158:159]
	v_pk_fma_f32 v[52:53], v[156:157], v[52:53], v[160:161]
	v_pk_fma_f32 v[50:51], v[150:151], v[62:63], v[50:51]
	v_pk_fma_f32 v[52:53], v[152:153], v[64:65], v[52:53]
	v_pk_fma_f32 v[50:51], v[146:147], v[166:167], v[50:51]
	v_pk_fma_f32 v[52:53], v[148:149], v[168:169], v[52:53]
	v_pk_fma_f32 v[62:63], v[154:155], v[62:63], v[158:159]
	v_pk_fma_f32 v[64:65], v[156:157], v[64:65], v[160:161]
	v_pk_fma_f32 v[62:63], v[150:151], v[166:167], v[62:63]
	v_pk_fma_f32 v[64:65], v[152:153], v[168:169], v[64:65]
	v_pk_fma_f32 v[62:63], v[146:147], v[162:163], v[62:63]
	v_pk_fma_f32 v[64:65], v[148:149], v[164:165], v[64:65]
	s_cmp_lg_u32 s54, 0
	s_cbranch_scc1 .Lnepib_np1
	v_cmp_eq_u32_e32 vcc, 0, v224
	s_and_saveexec_b64 s[8:9], vcc
	s_add_u32 s52, s88, 0x2d00000
	s_addc_u32 s53, s89, 0
	global_store_dwordx4 v228, v[62:65], s[52:53] offset:0
	global_store_dwordx4 v230, v[50:53], s[52:53] offset:0
	s_or_b64 exec, exec, s[8:9]
	s_nop 1
.Lnepib_np1:
	v_pk_mul_f32 v[30:31], v[62:63], s[100:101]
	v_pk_mul_f32 v[32:33], v[64:65], s[100:101]
	v_pk_mul_f32 v[54:55], v[50:51], s[100:101]
	v_pk_mul_f32 v[56:57], v[52:53], s[100:101]
	v_exp_f32_e32 v30, v30
	v_exp_f32_e32 v31, v31
	v_exp_f32_e32 v32, v32
	v_exp_f32_e32 v33, v33
	v_exp_f32_e32 v54, v54
	v_exp_f32_e32 v55, v55
	v_exp_f32_e32 v56, v56
	v_exp_f32_e32 v57, v57
	v_pk_add_f32 v[30:31], v[30:31], s[98:99]
	v_pk_add_f32 v[32:33], v[32:33], s[98:99]
	v_pk_add_f32 v[54:55], v[54:55], s[98:99]
	v_pk_add_f32 v[56:57], v[56:57], s[98:99]
	v_rcp_f32_e32 v30, v30
	v_rcp_f32_e32 v31, v31
	v_rcp_f32_e32 v32, v32
	v_rcp_f32_e32 v33, v33
	v_rcp_f32_e32 v54, v54
	v_rcp_f32_e32 v55, v55
	v_rcp_f32_e32 v56, v56
	v_rcp_f32_e32 v57, v57
	v_pk_mul_f32 v[62:63], v[62:63], v[134:135]
	v_pk_mul_f32 v[64:65], v[64:65], v[136:137]
	v_pk_mul_f32 v[50:51], v[50:51], v[130:131]
	v_pk_mul_f32 v[52:53], v[52:53], v[132:133]
	v_pk_mul_f32 v[62:63], v[62:63], v[30:31]
	v_pk_mul_f32 v[64:65], v[64:65], v[32:33]
	v_pk_mul_f32 v[50:51], v[50:51], v[54:55]
	v_pk_mul_f32 v[52:53], v[52:53], v[56:57]
	v_pk_mul_f32 v[30:31], v[46:47], s[100:101]
	v_pk_mul_f32 v[32:33], v[48:49], s[100:101]
	v_pk_mul_f32 v[54:55], v[142:143], s[100:101]
	v_pk_mul_f32 v[56:57], v[144:145], s[100:101]
	v_exp_f32_e32 v30, v30
	v_exp_f32_e32 v31, v31
	v_exp_f32_e32 v32, v32
	v_exp_f32_e32 v33, v33
	v_exp_f32_e32 v54, v54
	v_exp_f32_e32 v55, v55
	v_exp_f32_e32 v56, v56
	v_exp_f32_e32 v57, v57
	v_pk_add_f32 v[30:31], v[30:31], s[98:99]
	v_pk_add_f32 v[32:33], v[32:33], s[98:99]
	v_pk_add_f32 v[54:55], v[54:55], s[98:99]
	v_pk_add_f32 v[56:57], v[56:57], s[98:99]
	v_rcp_f32_e32 v30, v30
	v_rcp_f32_e32 v31, v31
	v_rcp_f32_e32 v32, v32
	v_rcp_f32_e32 v33, v33
	v_rcp_f32_e32 v54, v54
	v_rcp_f32_e32 v55, v55
	v_rcp_f32_e32 v56, v56
	v_rcp_f32_e32 v57, v57
	v_pk_mul_f32 v[46:47], v[46:47], v[78:79]
	v_pk_mul_f32 v[48:49], v[48:49], v[80:81]
	v_pk_mul_f32 v[142:143], v[142:143], v[138:139]
	v_pk_mul_f32 v[144:145], v[144:145], v[140:141]
	v_pk_mul_f32 v[46:47], v[46:47], v[30:31]
	v_pk_mul_f32 v[48:49], v[48:49], v[32:33]
	v_pk_mul_f32 v[142:143], v[142:143], v[54:55]
	v_pk_mul_f32 v[144:145], v[144:145], v[56:57]
	s_waitcnt lgkmcnt(0)
	ds_read_b128 v[146:149], v226 offset:16
	ds_read_b128 v[150:153], v226 offset:1040
	ds_read_b128 v[154:157], v226 offset:2064
	ds_read_b128 v[158:161], v226 offset:3088
	s_cmp_eq_u32 s54, 0
	s_cbranch_scc1 .Lnepib_z3
	ds_read_b128 v[162:165], v227 offset:16
	ds_read_b128 v[166:169], v227 offset:1040
	s_branch .Lnepib_j3

.Lnepib_j3:
	v_mov_b32_dpp v118, v66 row_shr:1 row_mask:0xf bank_mask:0xf
	v_mov_b32_dpp v122, v98 row_shr:1 row_mask:0xf bank_mask:0xf
	v_mov_b32_dpp v119, v67 row_shr:1 row_mask:0xf bank_mask:0xf
	v_mov_b32_dpp v123, v99 row_shr:1 row_mask:0xf bank_mask:0xf
	v_mov_b32_dpp v120, v68 row_shr:1 row_mask:0xf bank_mask:0xf
	v_mov_b32_dpp v124, v100 row_shr:1 row_mask:0xf bank_mask:0xf
	v_mov_b32_dpp v121, v69 row_shr:1 row_mask:0xf bank_mask:0xf
	v_mov_b32_dpp v125, v101 row_shr:1 row_mask:0xf bank_mask:0xf
	v_pk_fma_f32 v[98:99], v[204:205], v[98:99], v[208:209]
	v_pk_fma_f32 v[100:101], v[206:207], v[100:101], v[210:211]
	v_pk_fma_f32 v[98:99], v[200:201], v[66:67], v[98:99]
	v_pk_fma_f32 v[100:101], v[202:203], v[68:69], v[100:101]
	v_pk_fma_f32 v[98:99], v[196:197], v[70:71], v[98:99]
	v_pk_fma_f32 v[100:101], v[198:199], v[72:73], v[100:101]
	v_pk_fma_f32 v[66:67], v[204:205], v[66:67], v[208:209]
	v_pk_fma_f32 v[68:69], v[206:207], v[68:69], v[210:211]
	v_pk_fma_f32 v[66:67], v[200:201], v[70:71], v[66:67]
	v_pk_fma_f32 v[68:69], v[202:203], v[72:73], v[68:69]
	v_pk_fma_f32 v[66:67], v[196:197], v[74:75], v[66:67]
	v_pk_fma_f32 v[68:69], v[198:199], v[76:77], v[68:69]
	v_pk_fma_f32 v[70:71], v[204:205], v[70:71], v[208:209]
	v_pk_fma_f32 v[72:73], v[206:207], v[72:73], v[210:211]
	v_pk_fma_f32 v[70:71], v[200:201], v[74:75], v[70:71]
	v_pk_fma_f32 v[72:73], v[202:203], v[76:77], v[72:73]
	v_pk_fma_f32 v[70:71], v[196:197], v[122:123], v[70:71]
	v_pk_fma_f32 v[72:73], v[198:199], v[124:125], v[72:73]
	v_pk_fma_f32 v[74:75], v[204:205], v[74:75], v[208:209]
	v_pk_fma_f32 v[76:77], v[206:207], v[76:77], v[210:211]
	v_pk_fma_f32 v[74:75], v[200:201], v[122:123], v[74:75]
	v_pk_fma_f32 v[76:77], v[202:203], v[124:125], v[76:77]
	v_pk_fma_f32 v[74:75], v[196:197], v[118:119], v[74:75]
	v_pk_fma_f32 v[76:77], v[198:199], v[120:121], v[76:77]
	s_cmp_lg_u32 s54, 0
	s_cbranch_scc1 .Lnepib_np2
	v_cmp_eq_u32_e32 vcc, 0, v224
	s_and_saveexec_b64 s[8:9], vcc
	s_add_u32 s52, s88, 0x2d00000
	s_addc_u32 s53, s89, 0
	global_store_dwordx4 v229, v[74:77], s[52:53] offset:16
	global_store_dwordx4 v231, v[70:73], s[52:53] offset:16
	s_or_b64 exec, exec, s[8:9]
	s_nop 1
.Lnepib_np2:
	s_waitcnt lgkmcnt(0)
	ds_read_b128 v[196:199], v226 offset:512
	ds_read_b128 v[200:203], v226 offset:1536
	ds_read_b128 v[204:207], v226 offset:2560
	ds_read_b128 v[208:211], v226 offset:3584
	ds_read_b128 v[118:121], v227 offset:4608
	ds_read_b128 v[122:125], v227 offset:5632
	v_mov_b32_dpp v162, v34 row_shr:1 row_mask:0xf bank_mask:0xf
	v_mov_b32_dpp v166, v82 row_shr:1 row_mask:0xf bank_mask:0xf
	v_mov_b32_dpp v163, v35 row_shr:1 row_mask:0xf bank_mask:0xf
	v_mov_b32_dpp v167, v83 row_shr:1 row_mask:0xf bank_mask:0xf
	v_mov_b32_dpp v164, v36 row_shr:1 row_mask:0xf bank_mask:0xf
	v_mov_b32_dpp v168, v84 row_shr:1 row_mask:0xf bank_mask:0xf
	v_mov_b32_dpp v165, v37 row_shr:1 row_mask:0xf bank_mask:0xf
	v_mov_b32_dpp v169, v85 row_shr:1 row_mask:0xf bank_mask:0xf
	v_pk_fma_f32 v[82:83], v[154:155], v[82:83], v[158:159]
	v_pk_fma_f32 v[84:85], v[156:157], v[84:85], v[160:161]
	v_pk_fma_f32 v[82:83], v[150:151], v[34:35], v[82:83]
	v_pk_fma_f32 v[84:85], v[152:153], v[36:37], v[84:85]
	v_pk_fma_f32 v[82:83], v[146:147], v[38:39], v[82:83]
	v_pk_fma_f32 v[84:85], v[148:149], v[40:41], v[84:85]
	v_pk_fma_f32 v[34:35], v[154:155], v[34:35], v[158:159]
	v_pk_fma_f32 v[36:37], v[156:157], v[36:37], v[160:161]
	v_pk_fma_f32 v[34:35], v[150:151], v[38:39], v[34:35]
	v_pk_fma_f32 v[36:37], v[152:153], v[40:41], v[36:37]
	v_pk_fma_f32 v[34:35], v[146:147], v[42:43], v[34:35]
	v_pk_fma_f32 v[36:37], v[148:149], v[44:45], v[36:37]
	v_pk_fma_f32 v[38:39], v[154:155], v[38:39], v[158:159]
	v_pk_fma_f32 v[40:41], v[156:157], v[40:41], v[160:161]
	v_pk_fma_f32 v[38:39], v[150:151], v[42:43], v[38:39]
	v_pk_fma_f32 v[40:41], v[152:153], v[44:45], v[40:41]
	v_pk_fma_f32 v[38:39], v[146:147], v[166:167], v[38:39]
	v_pk_fma_f32 v[40:41], v[148:149], v[168:169], v[40:41]
	v_pk_fma_f32 v[42:43], v[154:155], v[42:43], v[158:159]
	v_pk_fma_f32 v[44:45], v[156:157], v[44:45], v[160:161]
	v_pk_fma_f32 v[42:43], v[150:151], v[166:167], v[42:43]
	v_pk_fma_f32 v[44:45], v[152:153], v[168:169], v[44:45]
	v_pk_fma_f32 v[42:43], v[146:147], v[162:163], v[42:43]
	v_pk_fma_f32 v[44:45], v[148:149], v[164:165], v[44:45]
	s_cmp_lg_u32 s54, 0
	s_cbranch_scc1 .Lnepib_np3
	v_cmp_eq_u32_e32 vcc, 0, v224
	s_and_saveexec_b64 s[8:9], vcc
	s_add_u32 s52, s88, 0x2d00000
	s_addc_u32 s53, s89, 0
	global_store_dwordx4 v228, v[42:45], s[52:53] offset:16
	global_store_dwordx4 v230, v[38:41], s[52:53] offset:16
	s_or_b64 exec, exec, s[8:9]
	s_nop 1
.Lnepib_np3:
	v_pk_mul_f32 v[30:31], v[42:43], s[100:101]
	v_pk_mul_f32 v[32:33], v[44:45], s[100:101]
	v_pk_mul_f32 v[54:55], v[38:39], s[100:101]
	v_pk_mul_f32 v[56:57], v[40:41], s[100:101]
	v_exp_f32_e32 v30, v30
	v_exp_f32_e32 v31, v31
	v_exp_f32_e32 v32, v32
	v_exp_f32_e32 v33, v33
	v_exp_f32_e32 v54, v54
	v_exp_f32_e32 v55, v55
	v_exp_f32_e32 v56, v56
	v_exp_f32_e32 v57, v57
	v_pk_add_f32 v[30:31], v[30:31], s[98:99]
	v_pk_add_f32 v[32:33], v[32:33], s[98:99]
	v_pk_add_f32 v[54:55], v[54:55], s[98:99]
	v_pk_add_f32 v[56:57], v[56:57], s[98:99]
	v_rcp_f32_e32 v30, v30
	v_rcp_f32_e32 v31, v31
	v_rcp_f32_e32 v32, v32
	v_rcp_f32_e32 v33, v33
	v_rcp_f32_e32 v54, v54
	v_rcp_f32_e32 v55, v55
	v_rcp_f32_e32 v56, v56
	v_rcp_f32_e32 v57, v57
	v_pk_mul_f32 v[42:43], v[42:43], v[74:75]
	v_pk_mul_f32 v[44:45], v[44:45], v[76:77]
	v_pk_mul_f32 v[38:39], v[38:39], v[70:71]
	v_pk_mul_f32 v[40:41], v[40:41], v[72:73]
	v_pk_mul_f32 v[42:43], v[42:43], v[30:31]
	v_pk_mul_f32 v[44:45], v[44:45], v[32:33]
	v_pk_mul_f32 v[38:39], v[38:39], v[54:55]
	v_pk_mul_f32 v[40:41], v[40:41], v[56:57]
	v_pk_mul_f32 v[30:31], v[34:35], s[100:101]
	v_pk_mul_f32 v[32:33], v[36:37], s[100:101]
	v_pk_mul_f32 v[54:55], v[82:83], s[100:101]
	v_pk_mul_f32 v[56:57], v[84:85], s[100:101]
	v_exp_f32_e32 v30, v30
	v_exp_f32_e32 v31, v31
	v_exp_f32_e32 v32, v32
	v_exp_f32_e32 v33, v33
	v_exp_f32_e32 v54, v54
	v_exp_f32_e32 v55, v55
	v_exp_f32_e32 v56, v56
	v_exp_f32_e32 v57, v57
	v_pk_add_f32 v[30:31], v[30:31], s[98:99]
	v_pk_add_f32 v[32:33], v[32:33], s[98:99]
	v_pk_add_f32 v[54:55], v[54:55], s[98:99]
	v_pk_add_f32 v[56:57], v[56:57], s[98:99]
	v_rcp_f32_e32 v30, v30
	v_rcp_f32_e32 v31, v31
	v_rcp_f32_e32 v32, v32
	v_rcp_f32_e32 v33, v33
	v_rcp_f32_e32 v54, v54
	v_rcp_f32_e32 v55, v55
	v_rcp_f32_e32 v56, v56
	v_rcp_f32_e32 v57, v57
	v_pk_mul_f32 v[34:35], v[34:35], v[66:67]
	v_pk_mul_f32 v[36:37], v[36:37], v[68:69]
	v_pk_mul_f32 v[82:83], v[82:83], v[98:99]
	v_pk_mul_f32 v[84:85], v[84:85], v[100:101]
	v_pk_mul_f32 v[34:35], v[34:35], v[30:31]
	v_pk_mul_f32 v[36:37], v[36:37], v[32:33]
	v_pk_mul_f32 v[82:83], v[82:83], v[54:55]
	v_pk_mul_f32 v[84:85], v[84:85], v[56:57]
	s_add_u32 s52, s88, 0x9000000
	s_addc_u32 s53, s89, 0
	v_cvt_pk_bf16_f32 v134, v62, v63
	v_cvt_pk_bf16_f32 v135, v64, v65
	v_cvt_pk_bf16_f32 v136, v42, v43
	v_cvt_pk_bf16_f32 v137, v44, v45
	global_store_dwordx4 v244, v[134:137], s[52:53]
	v_add_u32_e32 v244, 0x1600, v244
	v_cvt_pk_bf16_f32 v74, v50, v51
	v_cvt_pk_bf16_f32 v75, v52, v53
	v_cvt_pk_bf16_f32 v76, v38, v39
	v_cvt_pk_bf16_f32 v77, v40, v41
	global_store_dwordx4 v244, v[74:77], s[52:53]
	v_add_u32_e32 v244, 0x1600, v244
	v_cvt_pk_bf16_f32 v134, v46, v47
	v_cvt_pk_bf16_f32 v135, v48, v49
	v_cvt_pk_bf16_f32 v136, v34, v35
	v_cvt_pk_bf16_f32 v137, v36, v37
	global_store_dwordx4 v244, v[134:137], s[52:53]
	v_add_u32_e32 v244, 0x1600, v244
	v_cvt_pk_bf16_f32 v74, v142, v143
	v_cvt_pk_bf16_f32 v75, v144, v145
	v_cvt_pk_bf16_f32 v76, v82, v83
	v_cvt_pk_bf16_f32 v77, v84, v85
	global_store_dwordx4 v244, v[74:77], s[52:53]
	v_add_u32_e32 v244, 0xffffbe00, v244
	s_waitcnt lgkmcnt(0)
	ds_read_b128 v[146:149], v226 offset:0
	ds_read_b128 v[150:153], v226 offset:1024
	ds_read_b128 v[154:157], v226 offset:2048
	ds_read_b128 v[158:161], v226 offset:3072
	ds_read_b128 v[162:165], v227 offset:4096
	ds_read_b128 v[166:169], v227 offset:5120
	v_mov_b32_dpp v118, v102 row_shr:1 row_mask:0xf bank_mask:0xf
	v_mov_b32_dpp v122, v126 row_shr:1 row_mask:0xf bank_mask:0xf
	v_mov_b32_dpp v119, v103 row_shr:1 row_mask:0xf bank_mask:0xf
	v_mov_b32_dpp v123, v127 row_shr:1 row_mask:0xf bank_mask:0xf
	v_mov_b32_dpp v120, v104 row_shr:1 row_mask:0xf bank_mask:0xf
	v_mov_b32_dpp v124, v128 row_shr:1 row_mask:0xf bank_mask:0xf
	v_mov_b32_dpp v121, v105 row_shr:1 row_mask:0xf bank_mask:0xf
	v_mov_b32_dpp v125, v129 row_shr:1 row_mask:0xf bank_mask:0xf
	v_pk_fma_f32 v[126:127], v[204:205], v[126:127], v[208:209]
	v_pk_fma_f32 v[128:129], v[206:207], v[128:129], v[210:211]
	v_pk_fma_f32 v[126:127], v[200:201], v[102:103], v[126:127]
	v_pk_fma_f32 v[128:129], v[202:203], v[104:105], v[128:129]
	v_pk_fma_f32 v[126:127], v[196:197], v[106:107], v[126:127]
	v_pk_fma_f32 v[128:129], v[198:199], v[108:109], v[128:129]
	v_pk_fma_f32 v[102:103], v[204:205], v[102:103], v[208:209]
	v_pk_fma_f32 v[104:105], v[206:207], v[104:105], v[210:211]
	v_pk_fma_f32 v[102:103], v[200:201], v[106:107], v[102:103]
	v_pk_fma_f32 v[104:105], v[202:203], v[108:109], v[104:105]
	v_pk_fma_f32 v[102:103], v[196:197], v[110:111], v[102:103]
	v_pk_fma_f32 v[104:105], v[198:199], v[112:113], v[104:105]
	v_pk_fma_f32 v[106:107], v[204:205], v[106:107], v[208:209]
	v_pk_fma_f32 v[108:109], v[206:207], v[108:109], v[210:211]
	v_pk_fma_f32 v[106:107], v[200:201], v[110:111], v[106:107]
	v_pk_fma_f32 v[108:109], v[202:203], v[112:113], v[108:109]
	v_pk_fma_f32 v[106:107], v[196:197], v[122:123], v[106:107]
	v_pk_fma_f32 v[108:109], v[198:199], v[124:125], v[108:109]
	v_pk_fma_f32 v[110:111], v[204:205], v[110:111], v[208:209]
	v_pk_fma_f32 v[112:113], v[206:207], v[112:113], v[210:211]
	v_pk_fma_f32 v[110:111], v[200:201], v[122:123], v[110:111]
	v_pk_fma_f32 v[112:113], v[202:203], v[124:125], v[112:113]
	v_pk_fma_f32 v[110:111], v[196:197], v[118:119], v[110:111]
	v_pk_fma_f32 v[112:113], v[198:199], v[120:121], v[112:113]
	s_waitcnt lgkmcnt(0)
	ds_read_b128 v[196:199], v226 offset:528
	ds_read_b128 v[200:203], v226 offset:1552
	ds_read_b128 v[204:207], v226 offset:2576
	ds_read_b128 v[208:211], v226 offset:3600
	ds_read_b128 v[118:121], v227 offset:4624
	ds_read_b128 v[122:125], v227 offset:5648
	v_mov_b32_dpp v162, v86 row_shr:1 row_mask:0xf bank_mask:0xf
	v_mov_b32_dpp v166, v114 row_shr:1 row_mask:0xf bank_mask:0xf
	v_mov_b32_dpp v163, v87 row_shr:1 row_mask:0xf bank_mask:0xf
	v_mov_b32_dpp v167, v115 row_shr:1 row_mask:0xf bank_mask:0xf
	v_mov_b32_dpp v164, v88 row_shr:1 row_mask:0xf bank_mask:0xf
	v_mov_b32_dpp v168, v116 row_shr:1 row_mask:0xf bank_mask:0xf
	v_mov_b32_dpp v165, v89 row_shr:1 row_mask:0xf bank_mask:0xf
	v_mov_b32_dpp v169, v117 row_shr:1 row_mask:0xf bank_mask:0xf
	v_pk_fma_f32 v[114:115], v[154:155], v[114:115], v[158:159]
	v_pk_fma_f32 v[116:117], v[156:157], v[116:117], v[160:161]
	v_pk_fma_f32 v[114:115], v[150:151], v[86:87], v[114:115]
	v_pk_fma_f32 v[116:117], v[152:153], v[88:89], v[116:117]
	v_pk_fma_f32 v[114:115], v[146:147], v[90:91], v[114:115]
	v_pk_fma_f32 v[116:117], v[148:149], v[92:93], v[116:117]
	v_pk_fma_f32 v[86:87], v[154:155], v[86:87], v[158:159]
	v_pk_fma_f32 v[88:89], v[156:157], v[88:89], v[160:161]
	v_pk_fma_f32 v[86:87], v[150:151], v[90:91], v[86:87]
	v_pk_fma_f32 v[88:89], v[152:153], v[92:93], v[88:89]
	v_pk_fma_f32 v[86:87], v[146:147], v[94:95], v[86:87]
	v_pk_fma_f32 v[88:89], v[148:149], v[96:97], v[88:89]
	v_pk_fma_f32 v[90:91], v[154:155], v[90:91], v[158:159]
	v_pk_fma_f32 v[92:93], v[156:157], v[92:93], v[160:161]
	v_pk_fma_f32 v[90:91], v[150:151], v[94:95], v[90:91]
	v_pk_fma_f32 v[92:93], v[152:153], v[96:97], v[92:93]
	v_pk_fma_f32 v[90:91], v[146:147], v[166:167], v[90:91]
	v_pk_fma_f32 v[92:93], v[148:149], v[168:169], v[92:93]
	v_pk_fma_f32 v[94:95], v[154:155], v[94:95], v[158:159]
	v_pk_fma_f32 v[96:97], v[156:157], v[96:97], v[160:161]
	v_pk_fma_f32 v[94:95], v[150:151], v[166:167], v[94:95]
	v_pk_fma_f32 v[96:97], v[152:153], v[168:169], v[96:97]
	v_pk_fma_f32 v[94:95], v[146:147], v[162:163], v[94:95]
	v_pk_fma_f32 v[96:97], v[148:149], v[164:165], v[96:97]
	v_pk_mul_f32 v[30:31], v[94:95], s[100:101]
	v_pk_mul_f32 v[32:33], v[96:97], s[100:101]
	v_pk_mul_f32 v[54:55], v[90:91], s[100:101]
	v_pk_mul_f32 v[56:57], v[92:93], s[100:101]
	v_exp_f32_e32 v30, v30
	v_exp_f32_e32 v31, v31
	v_exp_f32_e32 v32, v32
	v_exp_f32_e32 v33, v33
	v_exp_f32_e32 v54, v54
	v_exp_f32_e32 v55, v55
	v_exp_f32_e32 v56, v56
	v_exp_f32_e32 v57, v57
	v_pk_add_f32 v[30:31], v[30:31], s[98:99]
	v_pk_add_f32 v[32:33], v[32:33], s[98:99]
	v_pk_add_f32 v[54:55], v[54:55], s[98:99]
	v_pk_add_f32 v[56:57], v[56:57], s[98:99]
	v_rcp_f32_e32 v30, v30
	v_rcp_f32_e32 v31, v31
	v_rcp_f32_e32 v32, v32
	v_rcp_f32_e32 v33, v33
	v_rcp_f32_e32 v54, v54
	v_rcp_f32_e32 v55, v55
	v_rcp_f32_e32 v56, v56
	v_rcp_f32_e32 v57, v57
	v_pk_mul_f32 v[94:95], v[94:95], v[110:111]
	v_pk_mul_f32 v[96:97], v[96:97], v[112:113]
	v_pk_mul_f32 v[90:91], v[90:91], v[106:107]
	v_pk_mul_f32 v[92:93], v[92:93], v[108:109]
	v_pk_mul_f32 v[94:95], v[94:95], v[30:31]
	v_pk_mul_f32 v[96:97], v[96:97], v[32:33]
	v_pk_mul_f32 v[90:91], v[90:91], v[54:55]
	v_pk_mul_f32 v[92:93], v[92:93], v[56:57]
	v_pk_mul_f32 v[30:31], v[86:87], s[100:101]
	v_pk_mul_f32 v[32:33], v[88:89], s[100:101]
	v_pk_mul_f32 v[54:55], v[114:115], s[100:101]
	v_pk_mul_f32 v[56:57], v[116:117], s[100:101]
	v_exp_f32_e32 v30, v30
	v_exp_f32_e32 v31, v31
	v_exp_f32_e32 v32, v32
	v_exp_f32_e32 v33, v33
	v_exp_f32_e32 v54, v54
	v_exp_f32_e32 v55, v55
	v_exp_f32_e32 v56, v56
	v_exp_f32_e32 v57, v57
	v_pk_add_f32 v[30:31], v[30:31], s[98:99]
	v_pk_add_f32 v[32:33], v[32:33], s[98:99]
	v_pk_add_f32 v[54:55], v[54:55], s[98:99]
	v_pk_add_f32 v[56:57], v[56:57], s[98:99]
	v_rcp_f32_e32 v30, v30
	v_rcp_f32_e32 v31, v31
	v_rcp_f32_e32 v32, v32
	v_rcp_f32_e32 v33, v33
	v_rcp_f32_e32 v54, v54
	v_rcp_f32_e32 v55, v55
	v_rcp_f32_e32 v56, v56
	v_rcp_f32_e32 v57, v57
	v_pk_mul_f32 v[86:87], v[86:87], v[102:103]
	v_pk_mul_f32 v[88:89], v[88:89], v[104:105]
	v_pk_mul_f32 v[114:115], v[114:115], v[126:127]
	v_pk_mul_f32 v[116:117], v[116:117], v[128:129]
	v_pk_mul_f32 v[86:87], v[86:87], v[30:31]
	v_pk_mul_f32 v[88:89], v[88:89], v[32:33]
	v_pk_mul_f32 v[114:115], v[114:115], v[54:55]
	v_pk_mul_f32 v[116:117], v[116:117], v[56:57]
	s_waitcnt lgkmcnt(0)
	ds_read_b128 v[146:149], v226 offset:16
	ds_read_b128 v[150:153], v226 offset:1040
	ds_read_b128 v[154:157], v226 offset:2064
	ds_read_b128 v[158:161], v226 offset:3088
	ds_read_b128 v[162:165], v227 offset:4112
	ds_read_b128 v[166:169], v227 offset:5136
	v_mov_b32_dpp v118, v14 row_shr:1 row_mask:0xf bank_mask:0xf
	v_mov_b32_dpp v122, v58 row_shr:1 row_mask:0xf bank_mask:0xf
	v_mov_b32_dpp v119, v15 row_shr:1 row_mask:0xf bank_mask:0xf
	v_mov_b32_dpp v123, v59 row_shr:1 row_mask:0xf bank_mask:0xf
	v_mov_b32_dpp v120, v16 row_shr:1 row_mask:0xf bank_mask:0xf
	v_mov_b32_dpp v124, v60 row_shr:1 row_mask:0xf bank_mask:0xf
	v_mov_b32_dpp v121, v17 row_shr:1 row_mask:0xf bank_mask:0xf
	v_mov_b32_dpp v125, v61 row_shr:1 row_mask:0xf bank_mask:0xf
	v_pk_fma_f32 v[58:59], v[204:205], v[58:59], v[208:209]
	v_pk_fma_f32 v[60:61], v[206:207], v[60:61], v[210:211]
	v_pk_fma_f32 v[58:59], v[200:201], v[14:15], v[58:59]
	v_pk_fma_f32 v[60:61], v[202:203], v[16:17], v[60:61]
	v_pk_fma_f32 v[58:59], v[196:197], v[18:19], v[58:59]
	v_pk_fma_f32 v[60:61], v[198:199], v[20:21], v[60:61]
	v_pk_fma_f32 v[14:15], v[204:205], v[14:15], v[208:209]
	v_pk_fma_f32 v[16:17], v[206:207], v[16:17], v[210:211]
	v_pk_fma_f32 v[14:15], v[200:201], v[18:19], v[14:15]
	v_pk_fma_f32 v[16:17], v[202:203], v[20:21], v[16:17]
	v_pk_fma_f32 v[14:15], v[196:197], v[22:23], v[14:15]
	v_pk_fma_f32 v[16:17], v[198:199], v[24:25], v[16:17]
	v_pk_fma_f32 v[18:19], v[204:205], v[18:19], v[208:209]
	v_pk_fma_f32 v[20:21], v[206:207], v[20:21], v[210:211]
	v_pk_fma_f32 v[18:19], v[200:201], v[22:23], v[18:19]
	v_pk_fma_f32 v[20:21], v[202:203], v[24:25], v[20:21]
	v_pk_fma_f32 v[18:19], v[196:197], v[122:123], v[18:19]
	v_pk_fma_f32 v[20:21], v[198:199], v[124:125], v[20:21]
	v_pk_fma_f32 v[22:23], v[204:205], v[22:23], v[208:209]
	v_pk_fma_f32 v[24:25], v[206:207], v[24:25], v[210:211]
	v_pk_fma_f32 v[22:23], v[200:201], v[122:123], v[22:23]
	v_pk_fma_f32 v[24:25], v[202:203], v[124:125], v[24:25]
	v_pk_fma_f32 v[22:23], v[196:197], v[118:119], v[22:23]
	v_pk_fma_f32 v[24:25], v[198:199], v[120:121], v[24:25]
	s_waitcnt lgkmcnt(0)
	v_mov_b32_dpp v162, v2 row_shr:1 row_mask:0xf bank_mask:0xf
	v_mov_b32_dpp v166, v26 row_shr:1 row_mask:0xf bank_mask:0xf
	v_mov_b32_dpp v163, v3 row_shr:1 row_mask:0xf bank_mask:0xf
	v_mov_b32_dpp v167, v27 row_shr:1 row_mask:0xf bank_mask:0xf
	v_mov_b32_dpp v164, v4 row_shr:1 row_mask:0xf bank_mask:0xf
	v_mov_b32_dpp v168, v28 row_shr:1 row_mask:0xf bank_mask:0xf
	v_mov_b32_dpp v165, v5 row_shr:1 row_mask:0xf bank_mask:0xf
	v_mov_b32_dpp v169, v29 row_shr:1 row_mask:0xf bank_mask:0xf
	v_pk_fma_f32 v[26:27], v[154:155], v[26:27], v[158:159]
	v_pk_fma_f32 v[28:29], v[156:157], v[28:29], v[160:161]
	v_pk_fma_f32 v[26:27], v[150:151], v[2:3], v[26:27]
	v_pk_fma_f32 v[28:29], v[152:153], v[4:5], v[28:29]
	v_pk_fma_f32 v[26:27], v[146:147], v[6:7], v[26:27]
	v_pk_fma_f32 v[28:29], v[148:149], v[8:9], v[28:29]
	v_pk_fma_f32 v[2:3], v[154:155], v[2:3], v[158:159]
	v_pk_fma_f32 v[4:5], v[156:157], v[4:5], v[160:161]
	v_pk_fma_f32 v[2:3], v[150:151], v[6:7], v[2:3]
	v_pk_fma_f32 v[4:5], v[152:153], v[8:9], v[4:5]
	v_pk_fma_f32 v[2:3], v[146:147], v[10:11], v[2:3]
	v_pk_fma_f32 v[4:5], v[148:149], v[12:13], v[4:5]
	v_pk_fma_f32 v[6:7], v[154:155], v[6:7], v[158:159]
	v_pk_fma_f32 v[8:9], v[156:157], v[8:9], v[160:161]
	v_pk_fma_f32 v[6:7], v[150:151], v[10:11], v[6:7]
	v_pk_fma_f32 v[8:9], v[152:153], v[12:13], v[8:9]
	v_pk_fma_f32 v[6:7], v[146:147], v[166:167], v[6:7]
	v_pk_fma_f32 v[8:9], v[148:149], v[168:169], v[8:9]
	v_pk_fma_f32 v[10:11], v[154:155], v[10:11], v[158:159]
	v_pk_fma_f32 v[12:13], v[156:157], v[12:13], v[160:161]
	v_pk_fma_f32 v[10:11], v[150:151], v[166:167], v[10:11]
	v_pk_fma_f32 v[12:13], v[152:153], v[168:169], v[12:13]
	v_pk_fma_f32 v[10:11], v[146:147], v[162:163], v[10:11]
	v_pk_fma_f32 v[12:13], v[148:149], v[164:165], v[12:13]
	v_pk_mul_f32 v[30:31], v[10:11], s[100:101]
	v_pk_mul_f32 v[32:33], v[12:13], s[100:101]
	v_pk_mul_f32 v[54:55], v[6:7], s[100:101]
	v_pk_mul_f32 v[56:57], v[8:9], s[100:101]
	v_exp_f32_e32 v30, v30
	v_exp_f32_e32 v31, v31
	v_exp_f32_e32 v32, v32
	v_exp_f32_e32 v33, v33
	v_exp_f32_e32 v54, v54
	v_exp_f32_e32 v55, v55
	v_exp_f32_e32 v56, v56
	v_exp_f32_e32 v57, v57
	v_pk_add_f32 v[30:31], v[30:31], s[98:99]
	v_pk_add_f32 v[32:33], v[32:33], s[98:99]
	v_pk_add_f32 v[54:55], v[54:55], s[98:99]
	v_pk_add_f32 v[56:57], v[56:57], s[98:99]
	v_rcp_f32_e32 v30, v30
	v_rcp_f32_e32 v31, v31
	v_rcp_f32_e32 v32, v32
	v_rcp_f32_e32 v33, v33
	v_rcp_f32_e32 v54, v54
	v_rcp_f32_e32 v55, v55
	v_rcp_f32_e32 v56, v56
	v_rcp_f32_e32 v57, v57
	v_pk_mul_f32 v[10:11], v[10:11], v[22:23]
	v_pk_mul_f32 v[12:13], v[12:13], v[24:25]
	v_pk_mul_f32 v[6:7], v[6:7], v[18:19]
	v_pk_mul_f32 v[8:9], v[8:9], v[20:21]
	v_pk_mul_f32 v[10:11], v[10:11], v[30:31]
	v_pk_mul_f32 v[12:13], v[12:13], v[32:33]
	v_pk_mul_f32 v[6:7], v[6:7], v[54:55]
	v_pk_mul_f32 v[8:9], v[8:9], v[56:57]
	v_pk_mul_f32 v[30:31], v[2:3], s[100:101]
	v_pk_mul_f32 v[32:33], v[4:5], s[100:101]
	v_pk_mul_f32 v[54:55], v[26:27], s[100:101]
	v_pk_mul_f32 v[56:57], v[28:29], s[100:101]
	v_exp_f32_e32 v30, v30
	v_exp_f32_e32 v31, v31
	v_exp_f32_e32 v32, v32
	v_exp_f32_e32 v33, v33
	v_exp_f32_e32 v54, v54
	v_exp_f32_e32 v55, v55
	v_exp_f32_e32 v56, v56
	v_exp_f32_e32 v57, v57
	v_pk_add_f32 v[30:31], v[30:31], s[98:99]
	v_pk_add_f32 v[32:33], v[32:33], s[98:99]
	v_pk_add_f32 v[54:55], v[54:55], s[98:99]
	v_pk_add_f32 v[56:57], v[56:57], s[98:99]
	v_rcp_f32_e32 v30, v30
	v_rcp_f32_e32 v31, v31
	v_rcp_f32_e32 v32, v32
	v_rcp_f32_e32 v33, v33
	v_rcp_f32_e32 v54, v54
	v_rcp_f32_e32 v55, v55
	v_rcp_f32_e32 v56, v56
	v_rcp_f32_e32 v57, v57
	v_pk_mul_f32 v[2:3], v[2:3], v[14:15]
	v_pk_mul_f32 v[4:5], v[4:5], v[16:17]
	v_pk_mul_f32 v[26:27], v[26:27], v[58:59]
	v_pk_mul_f32 v[28:29], v[28:29], v[60:61]
	v_pk_mul_f32 v[2:3], v[2:3], v[30:31]
	v_pk_mul_f32 v[4:5], v[4:5], v[32:33]
	v_pk_mul_f32 v[26:27], v[26:27], v[54:55]
	v_pk_mul_f32 v[28:29], v[28:29], v[56:57]
	v_add_u32_e32 v244, 0xb0000, v244
	v_cvt_pk_bf16_f32 v110, v94, v95
	v_cvt_pk_bf16_f32 v111, v96, v97
	v_cvt_pk_bf16_f32 v112, v10, v11
	v_cvt_pk_bf16_f32 v113, v12, v13
	global_store_dwordx4 v244, v[110:113], s[52:53]
	v_add_u32_e32 v244, 0x1600, v244
	v_cvt_pk_bf16_f32 v22, v90, v91
	v_cvt_pk_bf16_f32 v23, v92, v93
	v_cvt_pk_bf16_f32 v24, v6, v7
	v_cvt_pk_bf16_f32 v25, v8, v9
	global_store_dwordx4 v244, v[22:25], s[52:53]
	v_add_u32_e32 v244, 0x1600, v244
	v_cvt_pk_bf16_f32 v110, v86, v87
	v_cvt_pk_bf16_f32 v111, v88, v89
	v_cvt_pk_bf16_f32 v112, v2, v3
	v_cvt_pk_bf16_f32 v113, v4, v5
	global_store_dwordx4 v244, v[110:113], s[52:53]
	v_add_u32_e32 v244, 0x1600, v244
	v_cvt_pk_bf16_f32 v22, v114, v115
	v_cvt_pk_bf16_f32 v23, v116, v117
	v_cvt_pk_bf16_f32 v24, v26, v27
	v_cvt_pk_bf16_f32 v25, v28, v29
	global_store_dwordx4 v244, v[22:25], s[52:53]
	s_cmp_lg_u32 s54, 1
	s_cselect_b64 s[8:9], -1, 0
	s_andn2_b64 vcc, exec, s[4:5]
	s_mov_b64 s[4:5], -1
	s_cbranch_vccnz .LBB0_1313
	s_andn2_b64 vcc, exec, s[20:21]
	s_mov_b32 s43, s44
	s_mov_b64 s[30:31], s[16:17]
	s_mov_b64 s[4:5], s[40:41]
	s_cbranch_vccnz .LBB0_1350
	s_ashr_i32 s4, s44, 5
	s_mul_hi_i32 s5, s4, 0x5800
	s_mulk_i32 s4, 0x5800
	s_add_u32 s30, s3, s4
	s_addc_u32 s31, s6, s5
	s_mov_b32 s43, s42
	s_mov_b64 s[4:5], s[14:15]
